# speedup vs baseline: 1.1049x; 1.0000x over previous
;     ...
;   for (int kt = 0; kt < nk; ++kt) {
;     if (NST == 4 && kt + 2 < nk) asm volatile("s_waitcnt vmcnt(%0)" ::"n"(2 * NLD) : "memory");
;     else if (kt + 1 < nk) asm volatile("s_waitcnt vmcnt(%0)" ::"n"(NLD) : "memory");
;     else asm volatile("s_waitcnt vmcnt(0)" ::: "memory");
;     __builtin_amdgcn_s_barrier();
;     const char* st = smem + (kt % NST) * STAGE;
;     bf16x8 af[MS], bfr[4];
; #pragma unroll
;     for (int ms = 0; ms < MS; ++ms) af[ms] = *(const bf16x8*)(st + aoff_r + ms * 1024);
; #pragma unroll
;     for (int ns = 0; ns < 4; ++ns) bfr[ns] = *(const bf16x8*)(st + boff_r + ns * 1024);
;     asm volatile("" ::: "memory");
;     if (kt + NST - 1 < nk) ISSUE(kt + NST - 1)
;     __builtin_amdgcn_s_setprio(1);
; #pragma unroll
;     for (int ms = 0; ms < MS; ++ms)
; #pragma unroll
;       for (int ns = 0; ns < 4; ++ns) acc[ms][ns] = __builtin_amdgcn_mfma_f32_16x16x32_bf16(af[ms], bfr[ns], acc[ms][ns], 0, 0, 0);
;     __builtin_amdgcn_s_setprio(0);
;   }
.LBB0_58:
	s_mul_hi_u32 s10, s20, 0xaaaaaaab
	s_lshr_b32 s10, s10, 1
	s_mul_i32 s10, s10, 0x12000
	v_subrev_u32_e32 v130, s10, v242
	v_add_u32_e32 v139, s19, v243
	v_add_u32_e32 v130, v139, v130
	v_subrev_u32_e32 v138, s10, v244
	v_add_u32_e32 v150, v139, v138
	s_barrier
	ds_read_b128 v[138:141], v150 offset:16384
	ds_read_b128 v[142:145], v150 offset:17408
	ds_read_b128 v[146:149], v150 offset:18432
	ds_read_b128 v[150:153], v150 offset:19456
	ds_read_b128 v[174:177], v130
	ds_read_b128 v[170:173], v130 offset:1024
	ds_read_b128 v[166:169], v130 offset:2048
	ds_read_b128 v[162:165], v130 offset:3072
	ds_read_b128 v[158:161], v130 offset:4096
	ds_read_b128 v[154:157], v130 offset:5120
	ds_read_b128 v[134:137], v130 offset:6144
	ds_read_b128 v[130:133], v130 offset:7168
	s_cmp_gt_u32 s2, 29
	s_cbranch_scc1 .LBB0_53
	s_mul_i32 s11, s15, 0xab
	s_bfe_u32 s11, s11, 0x70009
	s_mul_i32 s11, s11, 3
	s_add_i32 s2, s4, 0x4000
	s_sub_i32 s11, s15, s11
	s_and_b32 s2, s2, 0x7c000
	s_and_b32 s11, s11, 0xff
	s_and_b32 s10, s4, 0x2000
	s_mulk_i32 s11, 0x6000
	s_lshl_b32 s2, s2, 1
	s_add_i32 s21, s13, s11
	s_setprio 1
	s_waitcnt lgkmcnt(7)
	v_mfma_f32_16x16x32_bf16 v[126:129], v[174:177], v[138:141], v[126:129]
	v_mfma_f32_16x16x32_bf16 v[122:125], v[174:177], v[142:145], v[122:125]
	v_mfma_f32_16x16x32_bf16 v[118:121], v[174:177], v[146:149], v[118:121]
	v_mfma_f32_16x16x32_bf16 v[114:117], v[174:177], v[150:153], v[114:117]
	s_waitcnt lgkmcnt(6)
	v_mfma_f32_16x16x32_bf16 v[110:113], v[170:173], v[138:141], v[110:113]
	v_mfma_f32_16x16x32_bf16 v[106:109], v[170:173], v[142:145], v[106:109]
	v_mfma_f32_16x16x32_bf16 v[102:105], v[170:173], v[146:149], v[102:105]
	v_mfma_f32_16x16x32_bf16 v[98:101], v[170:173], v[150:153], v[98:101]
	v_lshl_add_u64 v[214:215], v[196:197], 0, s[2:3]
	s_waitcnt lgkmcnt(5)
	v_mfma_f32_16x16x32_bf16 v[94:97], v[166:169], v[138:141], v[94:97]
	s_lshl_b32 s10, s10, 1
	v_mfma_f32_16x16x32_bf16 v[90:93], v[166:169], v[142:145], v[90:93]
	s_mov_b32 s11, s3
	v_mfma_f32_16x16x32_bf16 v[86:89], v[166:169], v[146:149], v[86:89]
	v_lshl_add_u64 v[214:215], v[214:215], 0, s[10:11]
	v_mfma_f32_16x16x32_bf16 v[82:85], v[166:169], v[150:153], v[82:85]
	s_mov_b32 m0, s21
	s_waitcnt lgkmcnt(4)
	v_mfma_f32_16x16x32_bf16 v[78:81], v[162:165], v[138:141], v[78:81]
	global_load_lds_dwordx4 v[214:215], off
	v_mfma_f32_16x16x32_bf16 v[74:77], v[162:165], v[142:145], v[74:77]
	v_lshl_add_u64 v[214:215], v[198:199], 0, s[2:3]
	v_mfma_f32_16x16x32_bf16 v[70:73], v[162:165], v[146:149], v[70:73]
	v_lshl_add_u64 v[214:215], v[214:215], 0, s[10:11]
	v_mfma_f32_16x16x32_bf16 v[66:69], v[162:165], v[150:153], v[66:69]
	s_add_i32 m0, s21, 0x1000
	s_waitcnt lgkmcnt(3)
	v_mfma_f32_16x16x32_bf16 v[62:65], v[158:161], v[138:141], v[62:65]
	global_load_lds_dwordx4 v[214:215], off
	v_mfma_f32_16x16x32_bf16 v[58:61], v[158:161], v[142:145], v[58:61]
	v_lshl_add_u64 v[214:215], v[200:201], 0, s[2:3]
	v_mfma_f32_16x16x32_bf16 v[54:57], v[158:161], v[146:149], v[54:57]
	v_lshl_add_u64 v[214:215], v[214:215], 0, s[10:11]
	v_mfma_f32_16x16x32_bf16 v[50:53], v[158:161], v[150:153], v[50:53]
	s_add_i32 m0, s21, 0x2000
	s_waitcnt lgkmcnt(2)
	v_mfma_f32_16x16x32_bf16 v[46:49], v[154:157], v[138:141], v[46:49]
	global_load_lds_dwordx4 v[214:215], off
	v_mfma_f32_16x16x32_bf16 v[42:45], v[154:157], v[142:145], v[42:45]
	v_lshl_add_u64 v[214:215], v[202:203], 0, s[2:3]
	v_mfma_f32_16x16x32_bf16 v[38:41], v[154:157], v[146:149], v[38:41]
	v_lshl_add_u64 v[214:215], v[214:215], 0, s[10:11]
	v_mfma_f32_16x16x32_bf16 v[34:37], v[154:157], v[150:153], v[34:37]
	s_add_i32 m0, s21, 0x3000
	s_waitcnt lgkmcnt(1)
	v_mfma_f32_16x16x32_bf16 v[30:33], v[134:137], v[138:141], v[30:33]
	global_load_lds_dwordx4 v[214:215], off
	v_mfma_f32_16x16x32_bf16 v[26:29], v[134:137], v[142:145], v[26:29]
	v_lshl_add_u64 v[214:215], v[206:207], 0, s[4:5]
	v_mfma_f32_16x16x32_bf16 v[22:25], v[134:137], v[146:149], v[22:25]
	s_add_i32 m0, s21, 0x4000
	v_mfma_f32_16x16x32_bf16 v[18:21], v[134:137], v[150:153], v[18:21]
	global_load_lds_dwordx4 v[214:215], off
	s_waitcnt lgkmcnt(0)
	v_mfma_f32_16x16x32_bf16 v[14:17], v[130:133], v[138:141], v[14:17]
	v_lshl_add_u64 v[214:215], v[204:205], 0, s[4:5]
	v_mfma_f32_16x16x32_bf16 v[10:13], v[130:133], v[142:145], v[10:13]
	s_add_i32 m0, s21, 0x5000
	v_mfma_f32_16x16x32_bf16 v[6:9], v[130:133], v[146:149], v[6:9]
	global_load_lds_dwordx4 v[214:215], off
	v_mfma_f32_16x16x32_bf16 v[2:5], v[130:133], v[150:153], v[2:5]
	s_setprio 0
	s_branch .Lgt_tail_1

;     ...
;   for (int kt = 0; kt < nk; ++kt) {
;     if (NST == 4 && kt + 2 < nk) asm volatile("s_waitcnt vmcnt(%0)" ::"n"(2 * NLD) : "memory");
;     else if (kt + 1 < nk) asm volatile("s_waitcnt vmcnt(%0)" ::"n"(NLD) : "memory");
;     else asm volatile("s_waitcnt vmcnt(0)" ::: "memory");
;     __builtin_amdgcn_s_barrier();
;     const char* st = smem + (kt % NST) * STAGE;
;     bf16x8 af[MS], bfr[4];
; #pragma unroll
;     for (int ms = 0; ms < MS; ++ms) af[ms] = *(const bf16x8*)(st + aoff_r + ms * 1024);
; #pragma unroll
;     for (int ns = 0; ns < 4; ++ns) bfr[ns] = *(const bf16x8*)(st + boff_r + ns * 1024);
;     asm volatile("" ::: "memory");
;     if (kt + NST - 1 < nk) ISSUE(kt + NST - 1)
;     __builtin_amdgcn_s_setprio(1);
; #pragma unroll
;     for (int ms = 0; ms < MS; ++ms)
; #pragma unroll
;       for (int ns = 0; ns < 4; ++ns) acc[ms][ns] = __builtin_amdgcn_mfma_f32_16x16x32_bf16(af[ms], bfr[ns], acc[ms][ns], 0, 0, 0);
;     __builtin_amdgcn_s_setprio(0);
;   }
.LBB0_87:
	s_mul_hi_u32 s10, s20, 0xaaaaaaab
	s_lshr_b32 s10, s10, 1
	s_mul_i32 s10, s10, 0x12000
	v_subrev_u32_e32 v130, s10, v239
	v_add_u32_e32 v139, s19, v240
	v_add_u32_e32 v130, v139, v130
	v_subrev_u32_e32 v138, s10, v241
	v_add_u32_e32 v150, v139, v138
	s_barrier
	ds_read_b128 v[138:141], v150 offset:16384
	ds_read_b128 v[142:145], v150 offset:17408
	ds_read_b128 v[146:149], v150 offset:18432
	ds_read_b128 v[150:153], v150 offset:19456
	ds_read_b128 v[174:177], v130
	ds_read_b128 v[170:173], v130 offset:1024
	ds_read_b128 v[166:169], v130 offset:2048
	ds_read_b128 v[162:165], v130 offset:3072
	ds_read_b128 v[158:161], v130 offset:4096
	ds_read_b128 v[154:157], v130 offset:5120
	ds_read_b128 v[134:137], v130 offset:6144
	ds_read_b128 v[130:133], v130 offset:7168
	s_cmp_gt_u32 s2, 29
	s_cbranch_scc1 .LBB0_82
	s_mul_i32 s11, s15, 0xab
	s_bfe_u32 s11, s11, 0x70009
	s_mul_i32 s11, s11, 3
	s_add_i32 s2, s4, 0x4000
	s_sub_i32 s11, s15, s11
	s_and_b32 s2, s2, 0x7c000
	s_and_b32 s11, s11, 0xff
	s_and_b32 s10, s4, 0x2000
	s_mulk_i32 s11, 0x6000
	s_lshl_b32 s2, s2, 1
	s_add_i32 s21, s13, s11
	s_setprio 1
	s_waitcnt lgkmcnt(7)
	v_mfma_f32_16x16x32_bf16 v[126:129], v[174:177], v[138:141], v[126:129]
	v_mfma_f32_16x16x32_bf16 v[122:125], v[174:177], v[142:145], v[122:125]
	v_mfma_f32_16x16x32_bf16 v[118:121], v[174:177], v[146:149], v[118:121]
	v_mfma_f32_16x16x32_bf16 v[114:117], v[174:177], v[150:153], v[114:117]
	s_waitcnt lgkmcnt(6)
	v_mfma_f32_16x16x32_bf16 v[110:113], v[170:173], v[138:141], v[110:113]
	v_mfma_f32_16x16x32_bf16 v[106:109], v[170:173], v[142:145], v[106:109]
	v_mfma_f32_16x16x32_bf16 v[102:105], v[170:173], v[146:149], v[102:105]
	v_mfma_f32_16x16x32_bf16 v[98:101], v[170:173], v[150:153], v[98:101]
	v_lshl_add_u64 v[214:215], v[196:197], 0, s[2:3]
	s_waitcnt lgkmcnt(5)
	v_mfma_f32_16x16x32_bf16 v[94:97], v[166:169], v[138:141], v[94:97]
	s_lshl_b32 s10, s10, 1
	v_mfma_f32_16x16x32_bf16 v[90:93], v[166:169], v[142:145], v[90:93]
	s_mov_b32 s11, s3
	v_mfma_f32_16x16x32_bf16 v[86:89], v[166:169], v[146:149], v[86:89]
	v_lshl_add_u64 v[214:215], v[214:215], 0, s[10:11]
	v_mfma_f32_16x16x32_bf16 v[82:85], v[166:169], v[150:153], v[82:85]
	s_mov_b32 m0, s21
	s_waitcnt lgkmcnt(4)
	v_mfma_f32_16x16x32_bf16 v[78:81], v[162:165], v[138:141], v[78:81]
	global_load_lds_dwordx4 v[214:215], off
	v_mfma_f32_16x16x32_bf16 v[74:77], v[162:165], v[142:145], v[74:77]
	v_lshl_add_u64 v[214:215], v[198:199], 0, s[2:3]
	v_mfma_f32_16x16x32_bf16 v[70:73], v[162:165], v[146:149], v[70:73]
	v_lshl_add_u64 v[214:215], v[214:215], 0, s[10:11]
	v_mfma_f32_16x16x32_bf16 v[66:69], v[162:165], v[150:153], v[66:69]
	s_add_i32 m0, s21, 0x1000
	s_waitcnt lgkmcnt(3)
	v_mfma_f32_16x16x32_bf16 v[62:65], v[158:161], v[138:141], v[62:65]
	global_load_lds_dwordx4 v[214:215], off
	v_mfma_f32_16x16x32_bf16 v[58:61], v[158:161], v[142:145], v[58:61]
	v_lshl_add_u64 v[214:215], v[200:201], 0, s[2:3]
	v_mfma_f32_16x16x32_bf16 v[54:57], v[158:161], v[146:149], v[54:57]
	v_lshl_add_u64 v[214:215], v[214:215], 0, s[10:11]
	v_mfma_f32_16x16x32_bf16 v[50:53], v[158:161], v[150:153], v[50:53]
	s_add_i32 m0, s21, 0x2000
	s_waitcnt lgkmcnt(2)
	v_mfma_f32_16x16x32_bf16 v[46:49], v[154:157], v[138:141], v[46:49]
	global_load_lds_dwordx4 v[214:215], off
	v_mfma_f32_16x16x32_bf16 v[42:45], v[154:157], v[142:145], v[42:45]
	v_lshl_add_u64 v[214:215], v[202:203], 0, s[2:3]
	v_mfma_f32_16x16x32_bf16 v[38:41], v[154:157], v[146:149], v[38:41]
	v_lshl_add_u64 v[214:215], v[214:215], 0, s[10:11]
	v_mfma_f32_16x16x32_bf16 v[34:37], v[154:157], v[150:153], v[34:37]
	s_add_i32 m0, s21, 0x3000
	s_waitcnt lgkmcnt(1)
	v_mfma_f32_16x16x32_bf16 v[30:33], v[134:137], v[138:141], v[30:33]
	global_load_lds_dwordx4 v[214:215], off
	v_mfma_f32_16x16x32_bf16 v[26:29], v[134:137], v[142:145], v[26:29]
	v_lshl_add_u64 v[214:215], v[206:207], 0, s[4:5]
	v_mfma_f32_16x16x32_bf16 v[22:25], v[134:137], v[146:149], v[22:25]
	s_add_i32 m0, s21, 0x4000
	v_mfma_f32_16x16x32_bf16 v[18:21], v[134:137], v[150:153], v[18:21]
	global_load_lds_dwordx4 v[214:215], off
	s_waitcnt lgkmcnt(0)
	v_mfma_f32_16x16x32_bf16 v[14:17], v[130:133], v[138:141], v[14:17]
	v_lshl_add_u64 v[214:215], v[204:205], 0, s[4:5]
	v_mfma_f32_16x16x32_bf16 v[10:13], v[130:133], v[142:145], v[10:13]
	s_add_i32 m0, s21, 0x5000
	v_mfma_f32_16x16x32_bf16 v[6:9], v[130:133], v[146:149], v[6:9]
	global_load_lds_dwordx4 v[214:215], off
	v_mfma_f32_16x16x32_bf16 v[2:5], v[130:133], v[150:153], v[2:5]
	s_setprio 0
	s_branch .Lgt_tail_2

;     ...
;   for (int kt = 0; kt < nk; ++kt) {
;     if (NST == 4 && kt + 2 < nk) asm volatile("s_waitcnt vmcnt(%0)" ::"n"(2 * NLD) : "memory");
;     else if (kt + 1 < nk) asm volatile("s_waitcnt vmcnt(%0)" ::"n"(NLD) : "memory");
;     else asm volatile("s_waitcnt vmcnt(0)" ::: "memory");
;     __builtin_amdgcn_s_barrier();
;     const char* st = smem + (kt % NST) * STAGE;
;     bf16x8 af[MS], bfr[4];
; #pragma unroll
;     for (int ms = 0; ms < MS; ++ms) af[ms] = *(const bf16x8*)(st + aoff_r + ms * 1024);
; #pragma unroll
;     for (int ns = 0; ns < 4; ++ns) bfr[ns] = *(const bf16x8*)(st + boff_r + ns * 1024);
;     asm volatile("" ::: "memory");
;     if (kt + NST - 1 < nk) ISSUE(kt + NST - 1)
;     __builtin_amdgcn_s_setprio(1);
; #pragma unroll
;     for (int ms = 0; ms < MS; ++ms)
; #pragma unroll
;       for (int ns = 0; ns < 4; ++ns) acc[ms][ns] = __builtin_amdgcn_mfma_f32_16x16x32_bf16(af[ms], bfr[ns], acc[ms][ns], 0, 0, 0);
;     __builtin_amdgcn_s_setprio(0);
;   }
.LBB0_126:
	s_mul_hi_u32 s8, s18, 0xaaaaaaab
	s_lshr_b32 s8, s8, 1
	s_mul_i32 s8, s8, 0x12000
	v_subrev_u32_e32 v130, s8, v240
	v_add_u32_e32 v139, s17, v241
	v_add_u32_e32 v130, v139, v130
	v_subrev_u32_e32 v138, s8, v242
	v_add_u32_e32 v150, v139, v138
	s_barrier
	ds_read_b128 v[138:141], v150 offset:16384
	ds_read_b128 v[142:145], v150 offset:17408
	ds_read_b128 v[146:149], v150 offset:18432
	ds_read_b128 v[150:153], v150 offset:19456
	ds_read_b128 v[174:177], v130
	ds_read_b128 v[170:173], v130 offset:1024
	ds_read_b128 v[166:169], v130 offset:2048
	ds_read_b128 v[162:165], v130 offset:3072
	ds_read_b128 v[158:161], v130 offset:4096
	ds_read_b128 v[154:157], v130 offset:5120
	ds_read_b128 v[134:137], v130 offset:6144
	ds_read_b128 v[130:133], v130 offset:7168
	s_cmpk_gt_u32 s2, 0x55
	s_cbranch_scc1 .LBB0_121
	s_mul_i32 s9, s16, 0xab
	s_bfe_u32 s9, s9, 0x70009
	s_mul_i32 s9, s9, 3
	s_add_i32 s2, s4, 0x4000
	s_sub_i32 s9, s16, s9
	s_and_b32 s2, s2, 0x1fc000
	s_and_b32 s9, s9, 0xff
	s_and_b32 s8, s4, 0x2000
	s_mulk_i32 s9, 0x6000
	s_lshl_b32 s2, s2, 1
	s_add_i32 s19, s15, s9
	s_setprio 1
	s_waitcnt lgkmcnt(7)
	v_mfma_f32_16x16x32_bf16 v[126:129], v[174:177], v[138:141], v[126:129]
	v_mfma_f32_16x16x32_bf16 v[122:125], v[174:177], v[142:145], v[122:125]
	v_mfma_f32_16x16x32_bf16 v[118:121], v[174:177], v[146:149], v[118:121]
	v_mfma_f32_16x16x32_bf16 v[114:117], v[174:177], v[150:153], v[114:117]
	s_waitcnt lgkmcnt(6)
	v_mfma_f32_16x16x32_bf16 v[110:113], v[170:173], v[138:141], v[110:113]
	v_mfma_f32_16x16x32_bf16 v[106:109], v[170:173], v[142:145], v[106:109]
	v_mfma_f32_16x16x32_bf16 v[102:105], v[170:173], v[146:149], v[102:105]
	v_mfma_f32_16x16x32_bf16 v[98:101], v[170:173], v[150:153], v[98:101]
	v_lshl_add_u64 v[214:215], v[194:195], 0, s[2:3]
	s_waitcnt lgkmcnt(5)
	v_mfma_f32_16x16x32_bf16 v[94:97], v[166:169], v[138:141], v[94:97]
	s_lshl_b32 s8, s8, 1
	v_mfma_f32_16x16x32_bf16 v[90:93], v[166:169], v[142:145], v[90:93]
	s_mov_b32 s9, s3
	v_mfma_f32_16x16x32_bf16 v[86:89], v[166:169], v[146:149], v[86:89]
	v_lshl_add_u64 v[214:215], v[214:215], 0, s[8:9]
	v_mfma_f32_16x16x32_bf16 v[82:85], v[166:169], v[150:153], v[82:85]
	s_mov_b32 m0, s19
	s_waitcnt lgkmcnt(4)
	v_mfma_f32_16x16x32_bf16 v[78:81], v[162:165], v[138:141], v[78:81]
	global_load_lds_dwordx4 v[214:215], off
	v_mfma_f32_16x16x32_bf16 v[74:77], v[162:165], v[142:145], v[74:77]
	v_lshl_add_u64 v[214:215], v[196:197], 0, s[2:3]
	v_mfma_f32_16x16x32_bf16 v[70:73], v[162:165], v[146:149], v[70:73]
	v_lshl_add_u64 v[214:215], v[214:215], 0, s[8:9]
	v_mfma_f32_16x16x32_bf16 v[66:69], v[162:165], v[150:153], v[66:69]
	s_add_i32 m0, s19, 0x1000
	s_waitcnt lgkmcnt(3)
	v_mfma_f32_16x16x32_bf16 v[62:65], v[158:161], v[138:141], v[62:65]
	global_load_lds_dwordx4 v[214:215], off
	v_mfma_f32_16x16x32_bf16 v[58:61], v[158:161], v[142:145], v[58:61]
	v_lshl_add_u64 v[214:215], v[198:199], 0, s[2:3]
	v_mfma_f32_16x16x32_bf16 v[54:57], v[158:161], v[146:149], v[54:57]
	v_lshl_add_u64 v[214:215], v[214:215], 0, s[8:9]
	v_mfma_f32_16x16x32_bf16 v[50:53], v[158:161], v[150:153], v[50:53]
	s_add_i32 m0, s19, 0x2000
	s_waitcnt lgkmcnt(2)
	v_mfma_f32_16x16x32_bf16 v[46:49], v[154:157], v[138:141], v[46:49]
	global_load_lds_dwordx4 v[214:215], off
	v_mfma_f32_16x16x32_bf16 v[42:45], v[154:157], v[142:145], v[42:45]
	v_lshl_add_u64 v[214:215], v[200:201], 0, s[2:3]
	v_mfma_f32_16x16x32_bf16 v[38:41], v[154:157], v[146:149], v[38:41]
	v_lshl_add_u64 v[214:215], v[214:215], 0, s[8:9]
	v_mfma_f32_16x16x32_bf16 v[34:37], v[154:157], v[150:153], v[34:37]
	s_add_i32 m0, s19, 0x3000
	s_waitcnt lgkmcnt(1)
	v_mfma_f32_16x16x32_bf16 v[30:33], v[134:137], v[138:141], v[30:33]
	global_load_lds_dwordx4 v[214:215], off
	v_mfma_f32_16x16x32_bf16 v[26:29], v[134:137], v[142:145], v[26:29]
	v_lshl_add_u64 v[214:215], v[202:203], 0, s[4:5]
	v_mfma_f32_16x16x32_bf16 v[22:25], v[134:137], v[146:149], v[22:25]
	s_add_i32 m0, s19, 0x4000
	v_mfma_f32_16x16x32_bf16 v[18:21], v[134:137], v[150:153], v[18:21]
	global_load_lds_dwordx4 v[214:215], off
	s_waitcnt lgkmcnt(0)
	v_mfma_f32_16x16x32_bf16 v[14:17], v[130:133], v[138:141], v[14:17]
	v_lshl_add_u64 v[214:215], v[204:205], 0, s[4:5]
	v_mfma_f32_16x16x32_bf16 v[10:13], v[130:133], v[142:145], v[10:13]
	s_add_i32 m0, s19, 0x5000
	v_mfma_f32_16x16x32_bf16 v[6:9], v[130:133], v[146:149], v[6:9]
	global_load_lds_dwordx4 v[214:215], off
	v_mfma_f32_16x16x32_bf16 v[2:5], v[130:133], v[150:153], v[2:5]
	s_setprio 0
	s_branch .Lgt_tail_3

;     ...
;   for (int kt = 0; kt < nk; ++kt) {
;     if (NST == 4 && kt + 2 < nk) asm volatile("s_waitcnt vmcnt(%0)" ::"n"(2 * NLD) : "memory");
;     else if (kt + 1 < nk) asm volatile("s_waitcnt vmcnt(%0)" ::"n"(NLD) : "memory");
;     else asm volatile("s_waitcnt vmcnt(0)" ::: "memory");
;     __builtin_amdgcn_s_barrier();
;     const char* st = smem + (kt % NST) * STAGE;
;     bf16x8 af[MS], bfr[4];
; #pragma unroll
;     for (int ms = 0; ms < MS; ++ms) af[ms] = *(const bf16x8*)(st + aoff_r + ms * 1024);
; #pragma unroll
;     for (int ns = 0; ns < 4; ++ns) bfr[ns] = *(const bf16x8*)(st + boff_r + ns * 1024);
;     asm volatile("" ::: "memory");
;     if (kt + NST - 1 < nk) ISSUE(kt + NST - 1)
;     __builtin_amdgcn_s_setprio(1);
; #pragma unroll
;     for (int ms = 0; ms < MS; ++ms)
; #pragma unroll
;       for (int ns = 0; ns < 4; ++ns) acc[ms][ns] = __builtin_amdgcn_mfma_f32_16x16x32_bf16(af[ms], bfr[ns], acc[ms][ns], 0, 0, 0);
;     __builtin_amdgcn_s_setprio(0);
.LBB0_155:
	s_mul_hi_u32 s8, s18, 0xaaaaaaab
	s_lshr_b32 s8, s8, 1
	s_mul_i32 s8, s8, 0x12000
	v_subrev_u32_e32 v130, s8, v236
	v_add_u32_e32 v139, s17, v237
	v_add_u32_e32 v130, v139, v130
	v_subrev_u32_e32 v138, s8, v238
	v_add_u32_e32 v150, v139, v138
	s_barrier
	ds_read_b128 v[138:141], v150 offset:16384
	ds_read_b128 v[142:145], v150 offset:17408
	ds_read_b128 v[146:149], v150 offset:18432
	ds_read_b128 v[150:153], v150 offset:19456
	ds_read_b128 v[174:177], v130
	ds_read_b128 v[170:173], v130 offset:1024
	ds_read_b128 v[166:169], v130 offset:2048
	ds_read_b128 v[162:165], v130 offset:3072
	ds_read_b128 v[158:161], v130 offset:4096
	ds_read_b128 v[154:157], v130 offset:5120
	ds_read_b128 v[134:137], v130 offset:6144
	ds_read_b128 v[130:133], v130 offset:7168
	s_cmpk_gt_u32 s2, 0x55
	s_cbranch_scc1 .LBB0_150
	s_mul_i32 s9, s16, 0xab
	s_bfe_u32 s9, s9, 0x70009
	s_mul_i32 s9, s9, 3
	s_add_i32 s2, s4, 0x4000
	s_sub_i32 s9, s16, s9
	s_and_b32 s2, s2, 0x1fc000
	s_and_b32 s9, s9, 0xff
	s_and_b32 s8, s4, 0x2000
	s_mulk_i32 s9, 0x6000
	s_lshl_b32 s2, s2, 1
	s_add_i32 s19, s15, s9
	s_setprio 1
	s_waitcnt lgkmcnt(7)
	v_mfma_f32_16x16x32_bf16 v[126:129], v[174:177], v[138:141], v[126:129]
	v_mfma_f32_16x16x32_bf16 v[122:125], v[174:177], v[142:145], v[122:125]
	v_mfma_f32_16x16x32_bf16 v[118:121], v[174:177], v[146:149], v[118:121]
	v_mfma_f32_16x16x32_bf16 v[114:117], v[174:177], v[150:153], v[114:117]
	s_waitcnt lgkmcnt(6)
	v_mfma_f32_16x16x32_bf16 v[110:113], v[170:173], v[138:141], v[110:113]
	v_mfma_f32_16x16x32_bf16 v[106:109], v[170:173], v[142:145], v[106:109]
	v_mfma_f32_16x16x32_bf16 v[102:105], v[170:173], v[146:149], v[102:105]
	v_mfma_f32_16x16x32_bf16 v[98:101], v[170:173], v[150:153], v[98:101]
	v_lshl_add_u64 v[214:215], v[194:195], 0, s[2:3]
	s_waitcnt lgkmcnt(5)
	v_mfma_f32_16x16x32_bf16 v[94:97], v[166:169], v[138:141], v[94:97]
	s_lshl_b32 s8, s8, 1
	v_mfma_f32_16x16x32_bf16 v[90:93], v[166:169], v[142:145], v[90:93]
	s_mov_b32 s9, s3
	v_mfma_f32_16x16x32_bf16 v[86:89], v[166:169], v[146:149], v[86:89]
	v_lshl_add_u64 v[214:215], v[214:215], 0, s[8:9]
	v_mfma_f32_16x16x32_bf16 v[82:85], v[166:169], v[150:153], v[82:85]
	s_mov_b32 m0, s19
	s_waitcnt lgkmcnt(4)
	v_mfma_f32_16x16x32_bf16 v[78:81], v[162:165], v[138:141], v[78:81]
	global_load_lds_dwordx4 v[214:215], off
	v_mfma_f32_16x16x32_bf16 v[74:77], v[162:165], v[142:145], v[74:77]
	v_lshl_add_u64 v[214:215], v[196:197], 0, s[2:3]
	v_mfma_f32_16x16x32_bf16 v[70:73], v[162:165], v[146:149], v[70:73]
	v_lshl_add_u64 v[214:215], v[214:215], 0, s[8:9]
	v_mfma_f32_16x16x32_bf16 v[66:69], v[162:165], v[150:153], v[66:69]
	s_add_i32 m0, s19, 0x1000
	s_waitcnt lgkmcnt(3)
	v_mfma_f32_16x16x32_bf16 v[62:65], v[158:161], v[138:141], v[62:65]
	global_load_lds_dwordx4 v[214:215], off
	v_mfma_f32_16x16x32_bf16 v[58:61], v[158:161], v[142:145], v[58:61]
	v_lshl_add_u64 v[214:215], v[198:199], 0, s[2:3]
	v_mfma_f32_16x16x32_bf16 v[54:57], v[158:161], v[146:149], v[54:57]
	v_lshl_add_u64 v[214:215], v[214:215], 0, s[8:9]
	v_mfma_f32_16x16x32_bf16 v[50:53], v[158:161], v[150:153], v[50:53]
	s_add_i32 m0, s19, 0x2000
	s_waitcnt lgkmcnt(2)
	v_mfma_f32_16x16x32_bf16 v[46:49], v[154:157], v[138:141], v[46:49]
	global_load_lds_dwordx4 v[214:215], off
	v_mfma_f32_16x16x32_bf16 v[42:45], v[154:157], v[142:145], v[42:45]
	v_lshl_add_u64 v[214:215], v[200:201], 0, s[2:3]
	v_mfma_f32_16x16x32_bf16 v[38:41], v[154:157], v[146:149], v[38:41]
	v_lshl_add_u64 v[214:215], v[214:215], 0, s[8:9]
	v_mfma_f32_16x16x32_bf16 v[34:37], v[154:157], v[150:153], v[34:37]
	s_add_i32 m0, s19, 0x3000
	s_waitcnt lgkmcnt(1)
	v_mfma_f32_16x16x32_bf16 v[30:33], v[134:137], v[138:141], v[30:33]
	global_load_lds_dwordx4 v[214:215], off
	v_mfma_f32_16x16x32_bf16 v[26:29], v[134:137], v[142:145], v[26:29]
	v_lshl_add_u64 v[214:215], v[202:203], 0, s[4:5]
	v_mfma_f32_16x16x32_bf16 v[22:25], v[134:137], v[146:149], v[22:25]
	s_add_i32 m0, s19, 0x4000
	v_mfma_f32_16x16x32_bf16 v[18:21], v[134:137], v[150:153], v[18:21]
	global_load_lds_dwordx4 v[214:215], off
	s_waitcnt lgkmcnt(0)
	v_mfma_f32_16x16x32_bf16 v[14:17], v[130:133], v[138:141], v[14:17]
	v_lshl_add_u64 v[214:215], v[204:205], 0, s[4:5]
	v_mfma_f32_16x16x32_bf16 v[10:13], v[130:133], v[142:145], v[10:13]
	s_add_i32 m0, s19, 0x5000
	v_mfma_f32_16x16x32_bf16 v[6:9], v[130:133], v[146:149], v[6:9]
	global_load_lds_dwordx4 v[214:215], off
	v_mfma_f32_16x16x32_bf16 v[2:5], v[130:133], v[150:153], v[2:5]
	s_setprio 0
	s_branch .Lgt_tail_4

;     ...
;   for (int kt = 0; kt < nk; ++kt) {
;     if (NST == 4 && kt + 2 < nk) asm volatile("s_waitcnt vmcnt(%0)" ::"n"(2 * NLD) : "memory");
;     else if (kt + 1 < nk) asm volatile("s_waitcnt vmcnt(%0)" ::"n"(NLD) : "memory");
;     else asm volatile("s_waitcnt vmcnt(0)" ::: "memory");
;     __builtin_amdgcn_s_barrier();
;     const char* st = smem + (kt % NST) * STAGE;
;     bf16x8 af[MS], bfr[4];
; #pragma unroll
;     for (int ms = 0; ms < MS; ++ms) af[ms] = *(const bf16x8*)(st + aoff_r + ms * 1024);
; #pragma unroll
;     for (int ns = 0; ns < 4; ++ns) bfr[ns] = *(const bf16x8*)(st + boff_r + ns * 1024);
;     asm volatile("" ::: "memory");
;     if (kt + NST - 1 < nk) ISSUE(kt + NST - 1)
;     __builtin_amdgcn_s_setprio(1);
; #pragma unroll
;     for (int ms = 0; ms < MS; ++ms)
; #pragma unroll
;       for (int ns = 0; ns < 4; ++ns) acc[ms][ns] = __builtin_amdgcn_mfma_f32_16x16x32_bf16(af[ms], bfr[ns], acc[ms][ns], 0, 0, 0);
;     __builtin_amdgcn_s_setprio(0);
.LBB0_185:
	s_mul_hi_u32 s10, s20, 0xaaaaaaab
	s_lshr_b32 s10, s10, 1
	s_mul_i32 s10, s10, 0x12000
	v_subrev_u32_e32 v130, s10, v187
	v_add_u32_e32 v139, s19, v189
	v_add_u32_e32 v130, v139, v130
	v_subrev_u32_e32 v138, s10, v238
	v_add_u32_e32 v150, v139, v138
	s_barrier
	ds_read_b128 v[138:141], v150 offset:16384
	ds_read_b128 v[142:145], v150 offset:17408
	ds_read_b128 v[146:149], v150 offset:18432
	ds_read_b128 v[150:153], v150 offset:19456
	ds_read_b128 v[174:177], v130
	ds_read_b128 v[170:173], v130 offset:1024
	ds_read_b128 v[166:169], v130 offset:2048
	ds_read_b128 v[162:165], v130 offset:3072
	ds_read_b128 v[158:161], v130 offset:4096
	ds_read_b128 v[154:157], v130 offset:5120
	ds_read_b128 v[134:137], v130 offset:6144
	ds_read_b128 v[130:133], v130 offset:7168
	s_cmp_gt_u32 s2, 29
	s_cbranch_scc1 .LBB0_180
	s_mul_i32 s11, s15, 0xab
	s_bfe_u32 s11, s11, 0x70009
	s_mul_i32 s11, s11, 3
	s_add_i32 s2, s4, 0x4000
	s_sub_i32 s11, s15, s11
	s_and_b32 s2, s2, 0x7c000
	s_and_b32 s11, s11, 0xff
	s_and_b32 s10, s4, 0x2000
	s_mulk_i32 s11, 0x6000
	s_lshl_b32 s2, s2, 1
	s_add_i32 s21, s13, s11
	s_setprio 1
	s_waitcnt lgkmcnt(7)
	v_mfma_f32_16x16x32_bf16 v[126:129], v[174:177], v[138:141], v[126:129]
	v_mfma_f32_16x16x32_bf16 v[122:125], v[174:177], v[142:145], v[122:125]
	v_mfma_f32_16x16x32_bf16 v[118:121], v[174:177], v[146:149], v[118:121]
	v_mfma_f32_16x16x32_bf16 v[114:117], v[174:177], v[150:153], v[114:117]
	s_waitcnt lgkmcnt(6)
	v_mfma_f32_16x16x32_bf16 v[110:113], v[170:173], v[138:141], v[110:113]
	v_mfma_f32_16x16x32_bf16 v[106:109], v[170:173], v[142:145], v[106:109]
	v_mfma_f32_16x16x32_bf16 v[102:105], v[170:173], v[146:149], v[102:105]
	v_mfma_f32_16x16x32_bf16 v[98:101], v[170:173], v[150:153], v[98:101]
	v_lshl_add_u64 v[214:215], v[198:199], 0, s[2:3]
	s_waitcnt lgkmcnt(5)
	v_mfma_f32_16x16x32_bf16 v[94:97], v[166:169], v[138:141], v[94:97]
	s_lshl_b32 s10, s10, 1
	v_mfma_f32_16x16x32_bf16 v[90:93], v[166:169], v[142:145], v[90:93]
	s_mov_b32 s11, s3
	v_mfma_f32_16x16x32_bf16 v[86:89], v[166:169], v[146:149], v[86:89]
	v_lshl_add_u64 v[214:215], v[214:215], 0, s[10:11]
	v_mfma_f32_16x16x32_bf16 v[82:85], v[166:169], v[150:153], v[82:85]
	s_mov_b32 m0, s21
	s_waitcnt lgkmcnt(4)
	v_mfma_f32_16x16x32_bf16 v[78:81], v[162:165], v[138:141], v[78:81]
	global_load_lds_dwordx4 v[214:215], off
	v_mfma_f32_16x16x32_bf16 v[74:77], v[162:165], v[142:145], v[74:77]
	v_lshl_add_u64 v[214:215], v[200:201], 0, s[2:3]
	v_mfma_f32_16x16x32_bf16 v[70:73], v[162:165], v[146:149], v[70:73]
	v_lshl_add_u64 v[214:215], v[214:215], 0, s[10:11]
	v_mfma_f32_16x16x32_bf16 v[66:69], v[162:165], v[150:153], v[66:69]
	s_add_i32 m0, s21, 0x1000
	s_waitcnt lgkmcnt(3)
	v_mfma_f32_16x16x32_bf16 v[62:65], v[158:161], v[138:141], v[62:65]
	global_load_lds_dwordx4 v[214:215], off
	v_mfma_f32_16x16x32_bf16 v[58:61], v[158:161], v[142:145], v[58:61]
	v_lshl_add_u64 v[214:215], v[202:203], 0, s[2:3]
	v_mfma_f32_16x16x32_bf16 v[54:57], v[158:161], v[146:149], v[54:57]
	v_lshl_add_u64 v[214:215], v[214:215], 0, s[10:11]
	v_mfma_f32_16x16x32_bf16 v[50:53], v[158:161], v[150:153], v[50:53]
	s_add_i32 m0, s21, 0x2000
	s_waitcnt lgkmcnt(2)
	v_mfma_f32_16x16x32_bf16 v[46:49], v[154:157], v[138:141], v[46:49]
	global_load_lds_dwordx4 v[214:215], off
	v_mfma_f32_16x16x32_bf16 v[42:45], v[154:157], v[142:145], v[42:45]
	v_lshl_add_u64 v[214:215], v[204:205], 0, s[2:3]
	v_mfma_f32_16x16x32_bf16 v[38:41], v[154:157], v[146:149], v[38:41]
	v_lshl_add_u64 v[214:215], v[214:215], 0, s[10:11]
	v_mfma_f32_16x16x32_bf16 v[34:37], v[154:157], v[150:153], v[34:37]
	s_add_i32 m0, s21, 0x3000
	s_waitcnt lgkmcnt(1)
	v_mfma_f32_16x16x32_bf16 v[30:33], v[134:137], v[138:141], v[30:33]
	global_load_lds_dwordx4 v[214:215], off
	v_mfma_f32_16x16x32_bf16 v[26:29], v[134:137], v[142:145], v[26:29]
	v_lshl_add_u64 v[214:215], v[208:209], 0, s[4:5]
	v_mfma_f32_16x16x32_bf16 v[22:25], v[134:137], v[146:149], v[22:25]
	s_add_i32 m0, s21, 0x4000
	v_mfma_f32_16x16x32_bf16 v[18:21], v[134:137], v[150:153], v[18:21]
	global_load_lds_dwordx4 v[214:215], off
	s_waitcnt lgkmcnt(0)
	v_mfma_f32_16x16x32_bf16 v[14:17], v[130:133], v[138:141], v[14:17]
	v_lshl_add_u64 v[214:215], v[206:207], 0, s[4:5]
	v_mfma_f32_16x16x32_bf16 v[10:13], v[130:133], v[142:145], v[10:13]
	s_add_i32 m0, s21, 0x5000
	v_mfma_f32_16x16x32_bf16 v[6:9], v[130:133], v[146:149], v[6:9]
	global_load_lds_dwordx4 v[214:215], off
	v_mfma_f32_16x16x32_bf16 v[2:5], v[130:133], v[150:153], v[2:5]
	s_setprio 0
	s_branch .Lgt_tail_5

;     ...
;   for (int kt = 0; kt < nk; ++kt) {
;     if (NST == 4 && kt + 2 < nk) asm volatile("s_waitcnt vmcnt(%0)" ::"n"(2 * NLD) : "memory");
;     else if (kt + 1 < nk) asm volatile("s_waitcnt vmcnt(%0)" ::"n"(NLD) : "memory");
;     else asm volatile("s_waitcnt vmcnt(0)" ::: "memory");
;     __builtin_amdgcn_s_barrier();
;     const char* st = smem + (kt % NST) * STAGE;
;     bf16x8 af[MS], bfr[4];
; #pragma unroll
;     for (int ms = 0; ms < MS; ++ms) af[ms] = *(const bf16x8*)(st + aoff_r + ms * 1024);
; #pragma unroll
;     for (int ns = 0; ns < 4; ++ns) bfr[ns] = *(const bf16x8*)(st + boff_r + ns * 1024);
;     asm volatile("" ::: "memory");
;     if (kt + NST - 1 < nk) ISSUE(kt + NST - 1)
;     __builtin_amdgcn_s_setprio(1);
; #pragma unroll
;     for (int ms = 0; ms < MS; ++ms)
; #pragma unroll
;       for (int ns = 0; ns < 4; ++ns) acc[ms][ns] = __builtin_amdgcn_mfma_f32_16x16x32_bf16(af[ms], bfr[ns], acc[ms][ns], 0, 0, 0);
;     __builtin_amdgcn_s_setprio(0);
.LBB0_242:
	s_mul_hi_u32 s12, s20, 0xaaaaaaab
	s_lshr_b32 s12, s12, 1
	s_mul_i32 s12, s12, 0x12000
	v_subrev_u32_e32 v130, s12, v240
	v_add_u32_e32 v139, s19, v241
	v_add_u32_e32 v130, v139, v130
	v_subrev_u32_e32 v138, s12, v242
	v_add_u32_e32 v150, v139, v138
	s_barrier
	ds_read_b128 v[138:141], v150 offset:16384
	ds_read_b128 v[142:145], v150 offset:17408
	ds_read_b128 v[146:149], v150 offset:18432
	ds_read_b128 v[150:153], v150 offset:19456
	ds_read_b128 v[174:177], v130
	ds_read_b128 v[170:173], v130 offset:1024
	ds_read_b128 v[166:169], v130 offset:2048
	ds_read_b128 v[162:165], v130 offset:3072
	ds_read_b128 v[158:161], v130 offset:4096
	ds_read_b128 v[154:157], v130 offset:5120
	ds_read_b128 v[134:137], v130 offset:6144
	ds_read_b128 v[130:133], v130 offset:7168
	s_cmp_gt_u32 s2, 5
	s_cbranch_scc1 .LBB0_237
	s_mul_i32 s13, s11, 0xab
	s_bfe_u32 s13, s13, 0x70009
	s_mul_i32 s13, s13, 3
	s_add_i32 s2, s4, 0x4000
	s_sub_i32 s13, s11, s13
	s_and_b32 s2, s2, 0x1c000
	s_and_b32 s13, s13, 0xff
	s_and_b32 s12, s4, 0x2000
	s_mulk_i32 s13, 0x6000
	s_lshl_b32 s2, s2, 1
	s_add_i32 s21, s9, s13
	s_setprio 1
	s_waitcnt lgkmcnt(7)
	v_mfma_f32_16x16x32_bf16 v[126:129], v[174:177], v[138:141], v[126:129]
	v_mfma_f32_16x16x32_bf16 v[122:125], v[174:177], v[142:145], v[122:125]
	v_mfma_f32_16x16x32_bf16 v[118:121], v[174:177], v[146:149], v[118:121]
	v_mfma_f32_16x16x32_bf16 v[114:117], v[174:177], v[150:153], v[114:117]
	s_waitcnt lgkmcnt(6)
	v_mfma_f32_16x16x32_bf16 v[110:113], v[170:173], v[138:141], v[110:113]
	v_mfma_f32_16x16x32_bf16 v[106:109], v[170:173], v[142:145], v[106:109]
	v_mfma_f32_16x16x32_bf16 v[102:105], v[170:173], v[146:149], v[102:105]
	v_mfma_f32_16x16x32_bf16 v[98:101], v[170:173], v[150:153], v[98:101]
	v_lshl_add_u64 v[214:215], v[194:195], 0, s[2:3]
	s_waitcnt lgkmcnt(5)
	v_mfma_f32_16x16x32_bf16 v[94:97], v[166:169], v[138:141], v[94:97]
	s_lshl_b32 s12, s12, 1
	v_mfma_f32_16x16x32_bf16 v[90:93], v[166:169], v[142:145], v[90:93]
	s_mov_b32 s13, s3
	v_mfma_f32_16x16x32_bf16 v[86:89], v[166:169], v[146:149], v[86:89]
	v_lshl_add_u64 v[214:215], v[214:215], 0, s[12:13]
	v_mfma_f32_16x16x32_bf16 v[82:85], v[166:169], v[150:153], v[82:85]
	s_mov_b32 m0, s21
	s_waitcnt lgkmcnt(4)
	v_mfma_f32_16x16x32_bf16 v[78:81], v[162:165], v[138:141], v[78:81]
	global_load_lds_dwordx4 v[214:215], off
	v_mfma_f32_16x16x32_bf16 v[74:77], v[162:165], v[142:145], v[74:77]
	v_lshl_add_u64 v[214:215], v[196:197], 0, s[2:3]
	v_mfma_f32_16x16x32_bf16 v[70:73], v[162:165], v[146:149], v[70:73]
	v_lshl_add_u64 v[214:215], v[214:215], 0, s[12:13]
	v_mfma_f32_16x16x32_bf16 v[66:69], v[162:165], v[150:153], v[66:69]
	s_add_i32 m0, s21, 0x1000
	s_waitcnt lgkmcnt(3)
	v_mfma_f32_16x16x32_bf16 v[62:65], v[158:161], v[138:141], v[62:65]
	global_load_lds_dwordx4 v[214:215], off
	v_mfma_f32_16x16x32_bf16 v[58:61], v[158:161], v[142:145], v[58:61]
	v_lshl_add_u64 v[214:215], v[198:199], 0, s[2:3]
	v_mfma_f32_16x16x32_bf16 v[54:57], v[158:161], v[146:149], v[54:57]
	v_lshl_add_u64 v[214:215], v[214:215], 0, s[12:13]
	v_mfma_f32_16x16x32_bf16 v[50:53], v[158:161], v[150:153], v[50:53]
	s_add_i32 m0, s21, 0x2000
	s_waitcnt lgkmcnt(2)
	v_mfma_f32_16x16x32_bf16 v[46:49], v[154:157], v[138:141], v[46:49]
	global_load_lds_dwordx4 v[214:215], off
	v_mfma_f32_16x16x32_bf16 v[42:45], v[154:157], v[142:145], v[42:45]
	v_lshl_add_u64 v[214:215], v[200:201], 0, s[2:3]
	v_mfma_f32_16x16x32_bf16 v[38:41], v[154:157], v[146:149], v[38:41]
	v_lshl_add_u64 v[214:215], v[214:215], 0, s[12:13]
	v_mfma_f32_16x16x32_bf16 v[34:37], v[154:157], v[150:153], v[34:37]
	s_add_i32 m0, s21, 0x3000
	s_waitcnt lgkmcnt(1)
	v_mfma_f32_16x16x32_bf16 v[30:33], v[134:137], v[138:141], v[30:33]
	global_load_lds_dwordx4 v[214:215], off
	v_mfma_f32_16x16x32_bf16 v[26:29], v[134:137], v[142:145], v[26:29]
	v_lshl_add_u64 v[214:215], v[204:205], 0, s[4:5]
	v_mfma_f32_16x16x32_bf16 v[22:25], v[134:137], v[146:149], v[22:25]
	s_add_i32 m0, s21, 0x4000
	v_mfma_f32_16x16x32_bf16 v[18:21], v[134:137], v[150:153], v[18:21]
	global_load_lds_dwordx4 v[214:215], off
	s_waitcnt lgkmcnt(0)
	v_mfma_f32_16x16x32_bf16 v[14:17], v[130:133], v[138:141], v[14:17]
	v_lshl_add_u64 v[214:215], v[202:203], 0, s[4:5]
	v_mfma_f32_16x16x32_bf16 v[10:13], v[130:133], v[142:145], v[10:13]
	s_add_i32 m0, s21, 0x5000
	v_mfma_f32_16x16x32_bf16 v[6:9], v[130:133], v[146:149], v[6:9]
	global_load_lds_dwordx4 v[214:215], off
	v_mfma_f32_16x16x32_bf16 v[2:5], v[130:133], v[150:153], v[2:5]
	s_setprio 0
	s_branch .Lgt_tail_7

;     ...
;   for (int kt = 0; kt < nk; ++kt) {
;     if (NST == 4 && kt + 2 < nk) asm volatile("s_waitcnt vmcnt(%0)" ::"n"(2 * NLD) : "memory");
;     else if (kt + 1 < nk) asm volatile("s_waitcnt vmcnt(%0)" ::"n"(NLD) : "memory");
;     else asm volatile("s_waitcnt vmcnt(0)" ::: "memory");
;     __builtin_amdgcn_s_barrier();
;     const char* st = smem + (kt % NST) * STAGE;
;     bf16x8 af[MS], bfr[4];
; #pragma unroll
;     for (int ms = 0; ms < MS; ++ms) af[ms] = *(const bf16x8*)(st + aoff_r + ms * 1024);
; #pragma unroll
;     for (int ns = 0; ns < 4; ++ns) bfr[ns] = *(const bf16x8*)(st + boff_r + ns * 1024);
;     asm volatile("" ::: "memory");
;     if (kt + NST - 1 < nk) ISSUE(kt + NST - 1)
;     __builtin_amdgcn_s_setprio(1);
; #pragma unroll
;     for (int ms = 0; ms < MS; ++ms)
; #pragma unroll
;       for (int ns = 0; ns < 4; ++ns) acc[ms][ns] = __builtin_amdgcn_mfma_f32_16x16x32_bf16(af[ms], bfr[ns], acc[ms][ns], 0, 0, 0);
;     __builtin_amdgcn_s_setprio(0);
.LBB0_271:
	s_mul_hi_u32 s12, s20, 0xaaaaaaab
	s_lshr_b32 s12, s12, 1
	s_mul_i32 s12, s12, 0x12000
	v_subrev_u32_e32 v130, s12, v236
	v_add_u32_e32 v139, s19, v237
	v_add_u32_e32 v130, v139, v130
	v_subrev_u32_e32 v138, s12, v238
	v_add_u32_e32 v150, v139, v138
	s_barrier
	ds_read_b128 v[138:141], v150 offset:16384
	ds_read_b128 v[142:145], v150 offset:17408
	ds_read_b128 v[146:149], v150 offset:18432
	ds_read_b128 v[150:153], v150 offset:19456
	ds_read_b128 v[174:177], v130
	ds_read_b128 v[170:173], v130 offset:1024
	ds_read_b128 v[166:169], v130 offset:2048
	ds_read_b128 v[162:165], v130 offset:3072
	ds_read_b128 v[158:161], v130 offset:4096
	ds_read_b128 v[154:157], v130 offset:5120
	ds_read_b128 v[134:137], v130 offset:6144
	ds_read_b128 v[130:133], v130 offset:7168
	s_cmp_gt_u32 s2, 5
	s_cbranch_scc1 .LBB0_266
	s_mul_i32 s13, s11, 0xab
	s_bfe_u32 s13, s13, 0x70009
	s_mul_i32 s13, s13, 3
	s_add_i32 s2, s4, 0x4000
	s_sub_i32 s13, s11, s13
	s_and_b32 s2, s2, 0x1c000
	s_and_b32 s13, s13, 0xff
	s_and_b32 s12, s4, 0x2000
	s_mulk_i32 s13, 0x6000
	s_lshl_b32 s2, s2, 1
	s_add_i32 s21, s9, s13
	s_setprio 1
	s_waitcnt lgkmcnt(7)
	v_mfma_f32_16x16x32_bf16 v[126:129], v[174:177], v[138:141], v[126:129]
	v_mfma_f32_16x16x32_bf16 v[122:125], v[174:177], v[142:145], v[122:125]
	v_mfma_f32_16x16x32_bf16 v[118:121], v[174:177], v[146:149], v[118:121]
	v_mfma_f32_16x16x32_bf16 v[114:117], v[174:177], v[150:153], v[114:117]
	s_waitcnt lgkmcnt(6)
	v_mfma_f32_16x16x32_bf16 v[110:113], v[170:173], v[138:141], v[110:113]
	v_mfma_f32_16x16x32_bf16 v[106:109], v[170:173], v[142:145], v[106:109]
	v_mfma_f32_16x16x32_bf16 v[102:105], v[170:173], v[146:149], v[102:105]
	v_mfma_f32_16x16x32_bf16 v[98:101], v[170:173], v[150:153], v[98:101]
	v_lshl_add_u64 v[214:215], v[194:195], 0, s[2:3]
	s_waitcnt lgkmcnt(5)
	v_mfma_f32_16x16x32_bf16 v[94:97], v[166:169], v[138:141], v[94:97]
	s_lshl_b32 s12, s12, 1
	v_mfma_f32_16x16x32_bf16 v[90:93], v[166:169], v[142:145], v[90:93]
	s_mov_b32 s13, s3
	v_mfma_f32_16x16x32_bf16 v[86:89], v[166:169], v[146:149], v[86:89]
	v_lshl_add_u64 v[214:215], v[214:215], 0, s[12:13]
	v_mfma_f32_16x16x32_bf16 v[82:85], v[166:169], v[150:153], v[82:85]
	s_mov_b32 m0, s21
	s_waitcnt lgkmcnt(4)
	v_mfma_f32_16x16x32_bf16 v[78:81], v[162:165], v[138:141], v[78:81]
	global_load_lds_dwordx4 v[214:215], off
	v_mfma_f32_16x16x32_bf16 v[74:77], v[162:165], v[142:145], v[74:77]
	v_lshl_add_u64 v[214:215], v[196:197], 0, s[2:3]
	v_mfma_f32_16x16x32_bf16 v[70:73], v[162:165], v[146:149], v[70:73]
	v_lshl_add_u64 v[214:215], v[214:215], 0, s[12:13]
	v_mfma_f32_16x16x32_bf16 v[66:69], v[162:165], v[150:153], v[66:69]
	s_add_i32 m0, s21, 0x1000
	s_waitcnt lgkmcnt(3)
	v_mfma_f32_16x16x32_bf16 v[62:65], v[158:161], v[138:141], v[62:65]
	global_load_lds_dwordx4 v[214:215], off
	v_mfma_f32_16x16x32_bf16 v[58:61], v[158:161], v[142:145], v[58:61]
	v_lshl_add_u64 v[214:215], v[198:199], 0, s[2:3]
	v_mfma_f32_16x16x32_bf16 v[54:57], v[158:161], v[146:149], v[54:57]
	v_lshl_add_u64 v[214:215], v[214:215], 0, s[12:13]
	v_mfma_f32_16x16x32_bf16 v[50:53], v[158:161], v[150:153], v[50:53]
	s_add_i32 m0, s21, 0x2000
	s_waitcnt lgkmcnt(2)
	v_mfma_f32_16x16x32_bf16 v[46:49], v[154:157], v[138:141], v[46:49]
	global_load_lds_dwordx4 v[214:215], off
	v_mfma_f32_16x16x32_bf16 v[42:45], v[154:157], v[142:145], v[42:45]
	v_lshl_add_u64 v[214:215], v[200:201], 0, s[2:3]
	v_mfma_f32_16x16x32_bf16 v[38:41], v[154:157], v[146:149], v[38:41]
	v_lshl_add_u64 v[214:215], v[214:215], 0, s[12:13]
	v_mfma_f32_16x16x32_bf16 v[34:37], v[154:157], v[150:153], v[34:37]
	s_add_i32 m0, s21, 0x3000
	s_waitcnt lgkmcnt(1)
	v_mfma_f32_16x16x32_bf16 v[30:33], v[134:137], v[138:141], v[30:33]
	global_load_lds_dwordx4 v[214:215], off
	v_mfma_f32_16x16x32_bf16 v[26:29], v[134:137], v[142:145], v[26:29]
	v_lshl_add_u64 v[214:215], v[204:205], 0, s[4:5]
	v_mfma_f32_16x16x32_bf16 v[22:25], v[134:137], v[146:149], v[22:25]
	s_add_i32 m0, s21, 0x4000
	v_mfma_f32_16x16x32_bf16 v[18:21], v[134:137], v[150:153], v[18:21]
	global_load_lds_dwordx4 v[214:215], off
	s_waitcnt lgkmcnt(0)
	v_mfma_f32_16x16x32_bf16 v[14:17], v[130:133], v[138:141], v[14:17]
	v_lshl_add_u64 v[214:215], v[202:203], 0, s[4:5]
	v_mfma_f32_16x16x32_bf16 v[10:13], v[130:133], v[142:145], v[10:13]
	s_add_i32 m0, s21, 0x5000
	v_mfma_f32_16x16x32_bf16 v[6:9], v[130:133], v[146:149], v[6:9]
	global_load_lds_dwordx4 v[214:215], off
	v_mfma_f32_16x16x32_bf16 v[2:5], v[130:133], v[150:153], v[2:5]
	s_setprio 0
	s_branch .Lgt_tail_8

;     ...
;   for (int kt = 0; kt < nk; ++kt) {
;     if (NST == 4 && kt + 2 < nk) asm volatile("s_waitcnt vmcnt(%0)" ::"n"(2 * NLD) : "memory");
;     else if (kt + 1 < nk) asm volatile("s_waitcnt vmcnt(%0)" ::"n"(NLD) : "memory");
;     else asm volatile("s_waitcnt vmcnt(0)" ::: "memory");
;     __builtin_amdgcn_s_barrier();
;     const char* st = smem + (kt % NST) * STAGE;
;     bf16x8 af[MS], bfr[4];
; #pragma unroll
;     for (int ms = 0; ms < MS; ++ms) af[ms] = *(const bf16x8*)(st + aoff_r + ms * 1024);
; #pragma unroll
;     for (int ns = 0; ns < 4; ++ns) bfr[ns] = *(const bf16x8*)(st + boff_r + ns * 1024);
;     asm volatile("" ::: "memory");
;     if (kt + NST - 1 < nk) ISSUE(kt + NST - 1)
;     __builtin_amdgcn_s_setprio(1);
; #pragma unroll
;     for (int ms = 0; ms < MS; ++ms)
; #pragma unroll
;       for (int ns = 0; ns < 4; ++ns) acc[ms][ns] = __builtin_amdgcn_mfma_f32_16x16x32_bf16(af[ms], bfr[ns], acc[ms][ns], 0, 0, 0);
;     __builtin_amdgcn_s_setprio(0);
.LBB0_310:
	s_mul_hi_u32 s10, s18, 0xaaaaaaab
	s_lshr_b32 s10, s10, 1
	s_mul_i32 s10, s10, 0x12000
	v_subrev_u32_e32 v130, s10, v240
	v_add_u32_e32 v139, s17, v241
	v_add_u32_e32 v130, v139, v130
	v_subrev_u32_e32 v138, s10, v242
	v_add_u32_e32 v150, v139, v138
	s_barrier
	ds_read_b128 v[138:141], v150 offset:16384
	ds_read_b128 v[142:145], v150 offset:17408
	ds_read_b128 v[146:149], v150 offset:18432
	ds_read_b128 v[150:153], v150 offset:19456
	ds_read_b128 v[174:177], v130
	ds_read_b128 v[170:173], v130 offset:1024
	ds_read_b128 v[166:169], v130 offset:2048
	ds_read_b128 v[162:165], v130 offset:3072
	ds_read_b128 v[158:161], v130 offset:4096
	ds_read_b128 v[154:157], v130 offset:5120
	ds_read_b128 v[134:137], v130 offset:6144
	ds_read_b128 v[130:133], v130 offset:7168
	s_cmp_gt_u32 s2, 29
	s_cbranch_scc1 .LBB0_305
	s_mul_i32 s11, s13, 0xab
	s_bfe_u32 s11, s11, 0x70009
	s_mul_i32 s11, s11, 3
	s_add_i32 s2, s4, 0x4000
	s_sub_i32 s11, s13, s11
	s_and_b32 s2, s2, 0x7c000
	s_and_b32 s11, s11, 0xff
	s_and_b32 s10, s4, 0x2000
	s_mulk_i32 s11, 0x6000
	s_lshl_b32 s2, s2, 1
	s_add_i32 s19, s9, s11
	s_setprio 1
	s_waitcnt lgkmcnt(7)
	v_mfma_f32_16x16x32_bf16 v[126:129], v[174:177], v[138:141], v[126:129]
	v_mfma_f32_16x16x32_bf16 v[122:125], v[174:177], v[142:145], v[122:125]
	v_mfma_f32_16x16x32_bf16 v[118:121], v[174:177], v[146:149], v[118:121]
	v_mfma_f32_16x16x32_bf16 v[114:117], v[174:177], v[150:153], v[114:117]
	s_waitcnt lgkmcnt(6)
	v_mfma_f32_16x16x32_bf16 v[110:113], v[170:173], v[138:141], v[110:113]
	v_mfma_f32_16x16x32_bf16 v[106:109], v[170:173], v[142:145], v[106:109]
	v_mfma_f32_16x16x32_bf16 v[102:105], v[170:173], v[146:149], v[102:105]
	v_mfma_f32_16x16x32_bf16 v[98:101], v[170:173], v[150:153], v[98:101]
	v_lshl_add_u64 v[214:215], v[194:195], 0, s[2:3]
	s_waitcnt lgkmcnt(5)
	v_mfma_f32_16x16x32_bf16 v[94:97], v[166:169], v[138:141], v[94:97]
	s_lshl_b32 s10, s10, 1
	v_mfma_f32_16x16x32_bf16 v[90:93], v[166:169], v[142:145], v[90:93]
	s_mov_b32 s11, s3
	v_mfma_f32_16x16x32_bf16 v[86:89], v[166:169], v[146:149], v[86:89]
	v_lshl_add_u64 v[214:215], v[214:215], 0, s[10:11]
	v_mfma_f32_16x16x32_bf16 v[82:85], v[166:169], v[150:153], v[82:85]
	s_mov_b32 m0, s19
	s_waitcnt lgkmcnt(4)
	v_mfma_f32_16x16x32_bf16 v[78:81], v[162:165], v[138:141], v[78:81]
	global_load_lds_dwordx4 v[214:215], off
	v_mfma_f32_16x16x32_bf16 v[74:77], v[162:165], v[142:145], v[74:77]
	v_lshl_add_u64 v[214:215], v[196:197], 0, s[2:3]
	v_mfma_f32_16x16x32_bf16 v[70:73], v[162:165], v[146:149], v[70:73]
	v_lshl_add_u64 v[214:215], v[214:215], 0, s[10:11]
	v_mfma_f32_16x16x32_bf16 v[66:69], v[162:165], v[150:153], v[66:69]
	s_add_i32 m0, s19, 0x1000
	s_waitcnt lgkmcnt(3)
	v_mfma_f32_16x16x32_bf16 v[62:65], v[158:161], v[138:141], v[62:65]
	global_load_lds_dwordx4 v[214:215], off
	v_mfma_f32_16x16x32_bf16 v[58:61], v[158:161], v[142:145], v[58:61]
	v_lshl_add_u64 v[214:215], v[198:199], 0, s[2:3]
	v_mfma_f32_16x16x32_bf16 v[54:57], v[158:161], v[146:149], v[54:57]
	v_lshl_add_u64 v[214:215], v[214:215], 0, s[10:11]
	v_mfma_f32_16x16x32_bf16 v[50:53], v[158:161], v[150:153], v[50:53]
	s_add_i32 m0, s19, 0x2000
	s_waitcnt lgkmcnt(2)
	v_mfma_f32_16x16x32_bf16 v[46:49], v[154:157], v[138:141], v[46:49]
	global_load_lds_dwordx4 v[214:215], off
	v_mfma_f32_16x16x32_bf16 v[42:45], v[154:157], v[142:145], v[42:45]
	v_lshl_add_u64 v[214:215], v[200:201], 0, s[2:3]
	v_mfma_f32_16x16x32_bf16 v[38:41], v[154:157], v[146:149], v[38:41]
	v_lshl_add_u64 v[214:215], v[214:215], 0, s[10:11]
	v_mfma_f32_16x16x32_bf16 v[34:37], v[154:157], v[150:153], v[34:37]
	s_add_i32 m0, s19, 0x3000
	s_waitcnt lgkmcnt(1)
	v_mfma_f32_16x16x32_bf16 v[30:33], v[134:137], v[138:141], v[30:33]
	global_load_lds_dwordx4 v[214:215], off
	v_mfma_f32_16x16x32_bf16 v[26:29], v[134:137], v[142:145], v[26:29]
	v_lshl_add_u64 v[214:215], v[202:203], 0, s[4:5]
	v_mfma_f32_16x16x32_bf16 v[22:25], v[134:137], v[146:149], v[22:25]
	s_add_i32 m0, s19, 0x4000
	v_mfma_f32_16x16x32_bf16 v[18:21], v[134:137], v[150:153], v[18:21]
	global_load_lds_dwordx4 v[214:215], off
	s_waitcnt lgkmcnt(0)
	v_mfma_f32_16x16x32_bf16 v[14:17], v[130:133], v[138:141], v[14:17]
	v_lshl_add_u64 v[214:215], v[204:205], 0, s[4:5]
	v_mfma_f32_16x16x32_bf16 v[10:13], v[130:133], v[142:145], v[10:13]
	s_add_i32 m0, s19, 0x5000
	v_mfma_f32_16x16x32_bf16 v[6:9], v[130:133], v[146:149], v[6:9]
	global_load_lds_dwordx4 v[214:215], off
	v_mfma_f32_16x16x32_bf16 v[2:5], v[130:133], v[150:153], v[2:5]
	s_setprio 0
	s_branch .Lgt_tail_9

;     ...
;   for (int kt = 0; kt < nk; ++kt) {
;     if (NST == 4 && kt + 2 < nk) asm volatile("s_waitcnt vmcnt(%0)" ::"n"(2 * NLD) : "memory");
;     else if (kt + 1 < nk) asm volatile("s_waitcnt vmcnt(%0)" ::"n"(NLD) : "memory");
;     else asm volatile("s_waitcnt vmcnt(0)" ::: "memory");
;     __builtin_amdgcn_s_barrier();
;     const char* st = smem + (kt % NST) * STAGE;
;     bf16x8 af[MS], bfr[4];
; #pragma unroll
;     for (int ms = 0; ms < MS; ++ms) af[ms] = *(const bf16x8*)(st + aoff_r + ms * 1024);
; #pragma unroll
;     for (int ns = 0; ns < 4; ++ns) bfr[ns] = *(const bf16x8*)(st + boff_r + ns * 1024);
;     asm volatile("" ::: "memory");
;     if (kt + NST - 1 < nk) ISSUE(kt + NST - 1)
;     __builtin_amdgcn_s_setprio(1);
; #pragma unroll
;     for (int ms = 0; ms < MS; ++ms)
; #pragma unroll
;       for (int ns = 0; ns < 4; ++ns) acc[ms][ns] = __builtin_amdgcn_mfma_f32_16x16x32_bf16(af[ms], bfr[ns], acc[ms][ns], 0, 0, 0);
;     __builtin_amdgcn_s_setprio(0);
.LBB0_339:
	s_mul_hi_u32 s10, s18, 0xaaaaaaab
	s_lshr_b32 s10, s10, 1
	s_mul_i32 s10, s10, 0x12000
	v_subrev_u32_e32 v130, s10, v236
	v_add_u32_e32 v139, s17, v237
	v_add_u32_e32 v130, v139, v130
	v_subrev_u32_e32 v138, s10, v238
	v_add_u32_e32 v150, v139, v138
	s_barrier
	ds_read_b128 v[138:141], v150 offset:16384
	ds_read_b128 v[142:145], v150 offset:17408
	ds_read_b128 v[146:149], v150 offset:18432
	ds_read_b128 v[150:153], v150 offset:19456
	ds_read_b128 v[174:177], v130
	ds_read_b128 v[170:173], v130 offset:1024
	ds_read_b128 v[166:169], v130 offset:2048
	ds_read_b128 v[162:165], v130 offset:3072
	ds_read_b128 v[158:161], v130 offset:4096
	ds_read_b128 v[154:157], v130 offset:5120
	ds_read_b128 v[134:137], v130 offset:6144
	ds_read_b128 v[130:133], v130 offset:7168
	s_cmp_gt_u32 s2, 29
	s_cbranch_scc1 .LBB0_334
	s_mul_i32 s11, s13, 0xab
	s_bfe_u32 s11, s11, 0x70009
	s_mul_i32 s11, s11, 3
	s_add_i32 s2, s4, 0x4000
	s_sub_i32 s11, s13, s11
	s_and_b32 s2, s2, 0x7c000
	s_and_b32 s11, s11, 0xff
	s_and_b32 s10, s4, 0x2000
	s_mulk_i32 s11, 0x6000
	s_lshl_b32 s2, s2, 1
	s_add_i32 s19, s9, s11
	s_setprio 1
	s_waitcnt lgkmcnt(7)
	v_mfma_f32_16x16x32_bf16 v[126:129], v[174:177], v[138:141], v[126:129]
	v_mfma_f32_16x16x32_bf16 v[122:125], v[174:177], v[142:145], v[122:125]
	v_mfma_f32_16x16x32_bf16 v[118:121], v[174:177], v[146:149], v[118:121]
	v_mfma_f32_16x16x32_bf16 v[114:117], v[174:177], v[150:153], v[114:117]
	s_waitcnt lgkmcnt(6)
	v_mfma_f32_16x16x32_bf16 v[110:113], v[170:173], v[138:141], v[110:113]
	v_mfma_f32_16x16x32_bf16 v[106:109], v[170:173], v[142:145], v[106:109]
	v_mfma_f32_16x16x32_bf16 v[102:105], v[170:173], v[146:149], v[102:105]
	v_mfma_f32_16x16x32_bf16 v[98:101], v[170:173], v[150:153], v[98:101]
	v_lshl_add_u64 v[214:215], v[194:195], 0, s[2:3]
	s_waitcnt lgkmcnt(5)
	v_mfma_f32_16x16x32_bf16 v[94:97], v[166:169], v[138:141], v[94:97]
	s_lshl_b32 s10, s10, 1
	v_mfma_f32_16x16x32_bf16 v[90:93], v[166:169], v[142:145], v[90:93]
	s_mov_b32 s11, s3
	v_mfma_f32_16x16x32_bf16 v[86:89], v[166:169], v[146:149], v[86:89]
	v_lshl_add_u64 v[214:215], v[214:215], 0, s[10:11]
	v_mfma_f32_16x16x32_bf16 v[82:85], v[166:169], v[150:153], v[82:85]
	s_mov_b32 m0, s19
	s_waitcnt lgkmcnt(4)
	v_mfma_f32_16x16x32_bf16 v[78:81], v[162:165], v[138:141], v[78:81]
	global_load_lds_dwordx4 v[214:215], off
	v_mfma_f32_16x16x32_bf16 v[74:77], v[162:165], v[142:145], v[74:77]
	v_lshl_add_u64 v[214:215], v[196:197], 0, s[2:3]
	v_mfma_f32_16x16x32_bf16 v[70:73], v[162:165], v[146:149], v[70:73]
	v_lshl_add_u64 v[214:215], v[214:215], 0, s[10:11]
	v_mfma_f32_16x16x32_bf16 v[66:69], v[162:165], v[150:153], v[66:69]
	s_add_i32 m0, s19, 0x1000
	s_waitcnt lgkmcnt(3)
	v_mfma_f32_16x16x32_bf16 v[62:65], v[158:161], v[138:141], v[62:65]
	global_load_lds_dwordx4 v[214:215], off
	v_mfma_f32_16x16x32_bf16 v[58:61], v[158:161], v[142:145], v[58:61]
	v_lshl_add_u64 v[214:215], v[198:199], 0, s[2:3]
	v_mfma_f32_16x16x32_bf16 v[54:57], v[158:161], v[146:149], v[54:57]
	v_lshl_add_u64 v[214:215], v[214:215], 0, s[10:11]
	v_mfma_f32_16x16x32_bf16 v[50:53], v[158:161], v[150:153], v[50:53]
	s_add_i32 m0, s19, 0x2000
	s_waitcnt lgkmcnt(2)
	v_mfma_f32_16x16x32_bf16 v[46:49], v[154:157], v[138:141], v[46:49]
	global_load_lds_dwordx4 v[214:215], off
	v_mfma_f32_16x16x32_bf16 v[42:45], v[154:157], v[142:145], v[42:45]
	v_lshl_add_u64 v[214:215], v[200:201], 0, s[2:3]
	v_mfma_f32_16x16x32_bf16 v[38:41], v[154:157], v[146:149], v[38:41]
	v_lshl_add_u64 v[214:215], v[214:215], 0, s[10:11]
	v_mfma_f32_16x16x32_bf16 v[34:37], v[154:157], v[150:153], v[34:37]
	s_add_i32 m0, s19, 0x3000
	s_waitcnt lgkmcnt(1)
	v_mfma_f32_16x16x32_bf16 v[30:33], v[134:137], v[138:141], v[30:33]
	global_load_lds_dwordx4 v[214:215], off
	v_mfma_f32_16x16x32_bf16 v[26:29], v[134:137], v[142:145], v[26:29]
	v_lshl_add_u64 v[214:215], v[202:203], 0, s[4:5]
	v_mfma_f32_16x16x32_bf16 v[22:25], v[134:137], v[146:149], v[22:25]
	s_add_i32 m0, s19, 0x4000
	v_mfma_f32_16x16x32_bf16 v[18:21], v[134:137], v[150:153], v[18:21]
	global_load_lds_dwordx4 v[214:215], off
	s_waitcnt lgkmcnt(0)
	v_mfma_f32_16x16x32_bf16 v[14:17], v[130:133], v[138:141], v[14:17]
	v_lshl_add_u64 v[214:215], v[204:205], 0, s[4:5]
	v_mfma_f32_16x16x32_bf16 v[10:13], v[130:133], v[142:145], v[10:13]
	s_add_i32 m0, s19, 0x5000
	v_mfma_f32_16x16x32_bf16 v[6:9], v[130:133], v[146:149], v[6:9]
	global_load_lds_dwordx4 v[214:215], off
	v_mfma_f32_16x16x32_bf16 v[2:5], v[130:133], v[150:153], v[2:5]
	s_setprio 0
	s_branch .Lgt_tail_10

;     ...
;   for (int kt = 0; kt < nk; ++kt) {
;     if (NST == 4 && kt + 2 < nk) asm volatile("s_waitcnt vmcnt(%0)" ::"n"(2 * NLD) : "memory");
;     else if (kt + 1 < nk) asm volatile("s_waitcnt vmcnt(%0)" ::"n"(NLD) : "memory");
;     else asm volatile("s_waitcnt vmcnt(0)" ::: "memory");
;     __builtin_amdgcn_s_barrier();
;     const char* st = smem + (kt % NST) * STAGE;
;     bf16x8 af[MS], bfr[4];
; #pragma unroll
;     for (int ms = 0; ms < MS; ++ms) af[ms] = *(const bf16x8*)(st + aoff_r + ms * 1024);
; #pragma unroll
;     for (int ns = 0; ns < 4; ++ns) bfr[ns] = *(const bf16x8*)(st + boff_r + ns * 1024);
;     asm volatile("" ::: "memory");
;     if (kt + NST - 1 < nk) ISSUE(kt + NST - 1)
;     __builtin_amdgcn_s_setprio(1);
; #pragma unroll
;     for (int ms = 0; ms < MS; ++ms)
; #pragma unroll
;       for (int ns = 0; ns < 4; ++ns) acc[ms][ns] = __builtin_amdgcn_mfma_f32_16x16x32_bf16(af[ms], bfr[ns], acc[ms][ns], 0, 0, 0);
;     __builtin_amdgcn_s_setprio(0);
.LBB0_607:
	s_mul_hi_u32 s10, s19, 0xaaaaaaab
	s_lshr_b32 s10, s10, 1
	s_mul_i32 s10, s10, 0x12000
	v_subrev_u32_e32 v130, s10, v244
	v_add_u32_e32 v139, s18, v245
	v_add_u32_e32 v130, v139, v130
	v_subrev_u32_e32 v138, s10, v246
	v_add_u32_e32 v150, v139, v138
	s_barrier
	ds_read_b128 v[138:141], v150 offset:16384
	ds_read_b128 v[142:145], v150 offset:17408
	ds_read_b128 v[146:149], v150 offset:18432
	ds_read_b128 v[150:153], v150 offset:19456
	ds_read_b128 v[174:177], v130
	ds_read_b128 v[170:173], v130 offset:1024
	ds_read_b128 v[166:169], v130 offset:2048
	ds_read_b128 v[162:165], v130 offset:3072
	ds_read_b128 v[158:161], v130 offset:4096
	ds_read_b128 v[154:157], v130 offset:5120
	ds_read_b128 v[134:137], v130 offset:6144
	ds_read_b128 v[130:133], v130 offset:7168
	s_cmp_gt_u32 s2, 29
	s_cbranch_scc1 .LBB0_602
	s_mul_i32 s11, s17, 0xab
	s_bfe_u32 s11, s11, 0x70009
	s_mul_i32 s11, s11, 3
	s_add_i32 s2, s4, 0x4000
	s_sub_i32 s11, s17, s11
	s_and_b32 s2, s2, 0x7c000
	s_and_b32 s11, s11, 0xff
	s_and_b32 s10, s4, 0x2000
	s_mulk_i32 s11, 0x6000
	s_lshl_b32 s2, s2, 1
	s_add_i32 s20, s13, s11
	s_setprio 1
	s_waitcnt lgkmcnt(7)
	v_mfma_f32_16x16x32_bf16 v[38:41], v[174:177], v[138:141], v[38:41]
	v_mfma_f32_16x16x32_bf16 v[122:125], v[174:177], v[142:145], v[122:125]
	v_mfma_f32_16x16x32_bf16 v[126:129], v[174:177], v[146:149], v[126:129]
	v_mfma_f32_16x16x32_bf16 v[118:121], v[174:177], v[150:153], v[118:121]
	s_waitcnt lgkmcnt(6)
	v_mfma_f32_16x16x32_bf16 v[26:29], v[170:173], v[138:141], v[26:29]
	v_mfma_f32_16x16x32_bf16 v[110:113], v[170:173], v[142:145], v[110:113]
	v_mfma_f32_16x16x32_bf16 v[114:117], v[170:173], v[146:149], v[114:117]
	v_mfma_f32_16x16x32_bf16 v[106:109], v[170:173], v[150:153], v[106:109]
	v_lshl_add_u64 v[214:215], v[198:199], 0, s[2:3]
	s_waitcnt lgkmcnt(5)
	v_mfma_f32_16x16x32_bf16 v[22:25], v[166:169], v[138:141], v[22:25]
	s_lshl_b32 s10, s10, 1
	v_mfma_f32_16x16x32_bf16 v[98:101], v[166:169], v[142:145], v[98:101]
	s_mov_b32 s11, s3
	v_mfma_f32_16x16x32_bf16 v[102:105], v[166:169], v[146:149], v[102:105]
	v_lshl_add_u64 v[214:215], v[214:215], 0, s[10:11]
	v_mfma_f32_16x16x32_bf16 v[94:97], v[166:169], v[150:153], v[94:97]
	s_mov_b32 m0, s20
	s_waitcnt lgkmcnt(4)
	v_mfma_f32_16x16x32_bf16 v[18:21], v[162:165], v[138:141], v[18:21]
	global_load_lds_dwordx4 v[214:215], off
	v_mfma_f32_16x16x32_bf16 v[86:89], v[162:165], v[142:145], v[86:89]
	v_lshl_add_u64 v[214:215], v[200:201], 0, s[2:3]
	v_mfma_f32_16x16x32_bf16 v[90:93], v[162:165], v[146:149], v[90:93]
	v_lshl_add_u64 v[214:215], v[214:215], 0, s[10:11]
	v_mfma_f32_16x16x32_bf16 v[82:85], v[162:165], v[150:153], v[82:85]
	s_add_i32 m0, s20, 0x1000
	s_waitcnt lgkmcnt(3)
	v_mfma_f32_16x16x32_bf16 v[14:17], v[158:161], v[138:141], v[14:17]
	global_load_lds_dwordx4 v[214:215], off
	v_mfma_f32_16x16x32_bf16 v[74:77], v[158:161], v[142:145], v[74:77]
	v_lshl_add_u64 v[214:215], v[202:203], 0, s[2:3]
	v_mfma_f32_16x16x32_bf16 v[78:81], v[158:161], v[146:149], v[78:81]
	v_lshl_add_u64 v[214:215], v[214:215], 0, s[10:11]
	v_mfma_f32_16x16x32_bf16 v[70:73], v[158:161], v[150:153], v[70:73]
	s_add_i32 m0, s20, 0x2000
	s_waitcnt lgkmcnt(2)
	v_mfma_f32_16x16x32_bf16 v[10:13], v[154:157], v[138:141], v[10:13]
	global_load_lds_dwordx4 v[214:215], off
	v_mfma_f32_16x16x32_bf16 v[62:65], v[154:157], v[142:145], v[62:65]
	v_lshl_add_u64 v[214:215], v[204:205], 0, s[2:3]
	v_mfma_f32_16x16x32_bf16 v[66:69], v[154:157], v[146:149], v[66:69]
	v_lshl_add_u64 v[214:215], v[214:215], 0, s[10:11]
	v_mfma_f32_16x16x32_bf16 v[58:61], v[154:157], v[150:153], v[58:61]
	s_add_i32 m0, s20, 0x3000
	s_waitcnt lgkmcnt(1)
	v_mfma_f32_16x16x32_bf16 v[6:9], v[134:137], v[138:141], v[6:9]
	global_load_lds_dwordx4 v[214:215], off
	v_mfma_f32_16x16x32_bf16 v[50:53], v[134:137], v[142:145], v[50:53]
	v_lshl_add_u64 v[214:215], v[208:209], 0, s[4:5]
	v_mfma_f32_16x16x32_bf16 v[54:57], v[134:137], v[146:149], v[54:57]
	s_add_i32 m0, s20, 0x4000
	v_mfma_f32_16x16x32_bf16 v[46:49], v[134:137], v[150:153], v[46:49]
	global_load_lds_dwordx4 v[214:215], off
	s_waitcnt lgkmcnt(0)
	v_mfma_f32_16x16x32_bf16 v[2:5], v[130:133], v[138:141], v[2:5]
	v_lshl_add_u64 v[214:215], v[206:207], 0, s[4:5]
	v_mfma_f32_16x16x32_bf16 v[34:37], v[130:133], v[142:145], v[34:37]
	s_add_i32 m0, s20, 0x5000
	v_mfma_f32_16x16x32_bf16 v[42:45], v[130:133], v[146:149], v[42:45]
	global_load_lds_dwordx4 v[214:215], off
	v_mfma_f32_16x16x32_bf16 v[30:33], v[130:133], v[150:153], v[30:33]
	s_setprio 0
	s_branch .Lgt_tail_11

;     ...
;   for (int kt = 0; kt < nk; ++kt) {
;     if (NST == 4 && kt + 2 < nk) asm volatile("s_waitcnt vmcnt(%0)" ::"n"(2 * NLD) : "memory");
;     else if (kt + 1 < nk) asm volatile("s_waitcnt vmcnt(%0)" ::"n"(NLD) : "memory");
;     else asm volatile("s_waitcnt vmcnt(0)" ::: "memory");
;     __builtin_amdgcn_s_barrier();
;     const char* st = smem + (kt % NST) * STAGE;
;     bf16x8 af[MS], bfr[4];
; #pragma unroll
;     for (int ms = 0; ms < MS; ++ms) af[ms] = *(const bf16x8*)(st + aoff_r + ms * 1024);
; #pragma unroll
;     for (int ns = 0; ns < 4; ++ns) bfr[ns] = *(const bf16x8*)(st + boff_r + ns * 1024);
;     asm volatile("" ::: "memory");
;     if (kt + NST - 1 < nk) ISSUE(kt + NST - 1)
;     __builtin_amdgcn_s_setprio(1);
; #pragma unroll
;     for (int ms = 0; ms < MS; ++ms)
; #pragma unroll
;       for (int ns = 0; ns < 4; ++ns) acc[ms][ns] = __builtin_amdgcn_mfma_f32_16x16x32_bf16(af[ms], bfr[ns], acc[ms][ns], 0, 0, 0);
;     __builtin_amdgcn_s_setprio(0);
.LBB0_1421:
	s_mul_hi_u32 s12, s19, 0xaaaaaaab
	s_lshr_b32 s12, s12, 1
	s_mul_i32 s12, s12, 0x12000
	v_subrev_u32_e32 v130, s12, v241
	v_add_u32_e32 v139, s18, v242
	v_add_u32_e32 v130, v139, v130
	v_subrev_u32_e32 v138, s12, v243
	v_add_u32_e32 v150, v139, v138
	s_barrier
	ds_read_b128 v[138:141], v150 offset:16384
	ds_read_b128 v[142:145], v150 offset:17408
	ds_read_b128 v[146:149], v150 offset:18432
	ds_read_b128 v[150:153], v150 offset:19456
	ds_read_b128 v[174:177], v130
	ds_read_b128 v[170:173], v130 offset:1024
	ds_read_b128 v[166:169], v130 offset:2048
	ds_read_b128 v[162:165], v130 offset:3072
	ds_read_b128 v[158:161], v130 offset:4096
	ds_read_b128 v[154:157], v130 offset:5120
	ds_read_b128 v[134:137], v130 offset:6144
	ds_read_b128 v[130:133], v130 offset:7168
	s_cmp_gt_u32 s2, 29
	s_cbranch_scc1 .LBB0_1416
	s_mul_i32 s13, s17, 0xab
	s_bfe_u32 s13, s13, 0x70009
	s_mul_i32 s13, s13, 3
	s_add_i32 s2, s4, 0x4000
	s_sub_i32 s13, s17, s13
	s_and_b32 s2, s2, 0x7c000
	s_and_b32 s13, s13, 0xff
	s_and_b32 s12, s4, 0x2000
	s_mulk_i32 s13, 0x6000
	s_lshl_b32 s2, s2, 1
	s_add_i32 s21, s11, s13
	s_setprio 1
	s_waitcnt lgkmcnt(7)
	v_mfma_f32_16x16x32_bf16 v[38:41], v[174:177], v[138:141], v[38:41]
	v_mfma_f32_16x16x32_bf16 v[122:125], v[174:177], v[142:145], v[122:125]
	v_mfma_f32_16x16x32_bf16 v[126:129], v[174:177], v[146:149], v[126:129]
	v_mfma_f32_16x16x32_bf16 v[118:121], v[174:177], v[150:153], v[118:121]
	s_waitcnt lgkmcnt(6)
	v_mfma_f32_16x16x32_bf16 v[26:29], v[170:173], v[138:141], v[26:29]
	v_mfma_f32_16x16x32_bf16 v[110:113], v[170:173], v[142:145], v[110:113]
	v_mfma_f32_16x16x32_bf16 v[114:117], v[170:173], v[146:149], v[114:117]
	v_mfma_f32_16x16x32_bf16 v[106:109], v[170:173], v[150:153], v[106:109]
	v_lshl_add_u64 v[244:245], v[198:199], 0, s[2:3]
	s_waitcnt lgkmcnt(5)
	v_mfma_f32_16x16x32_bf16 v[22:25], v[166:169], v[138:141], v[22:25]
	s_lshl_b32 s12, s12, 1
	v_mfma_f32_16x16x32_bf16 v[98:101], v[166:169], v[142:145], v[98:101]
	s_mov_b32 s13, s3
	v_mfma_f32_16x16x32_bf16 v[102:105], v[166:169], v[146:149], v[102:105]
	v_lshl_add_u64 v[244:245], v[244:245], 0, s[12:13]
	v_mfma_f32_16x16x32_bf16 v[94:97], v[166:169], v[150:153], v[94:97]
	s_mov_b32 m0, s21
	s_waitcnt lgkmcnt(4)
	v_mfma_f32_16x16x32_bf16 v[18:21], v[162:165], v[138:141], v[18:21]
	global_load_lds_dwordx4 v[244:245], off
	v_mfma_f32_16x16x32_bf16 v[86:89], v[162:165], v[142:145], v[86:89]
	v_lshl_add_u64 v[244:245], v[200:201], 0, s[2:3]
	v_mfma_f32_16x16x32_bf16 v[90:93], v[162:165], v[146:149], v[90:93]
	v_lshl_add_u64 v[244:245], v[244:245], 0, s[12:13]
	v_mfma_f32_16x16x32_bf16 v[82:85], v[162:165], v[150:153], v[82:85]
	s_add_i32 m0, s21, 0x1000
	s_waitcnt lgkmcnt(3)
	v_mfma_f32_16x16x32_bf16 v[14:17], v[158:161], v[138:141], v[14:17]
	global_load_lds_dwordx4 v[244:245], off
	v_mfma_f32_16x16x32_bf16 v[74:77], v[158:161], v[142:145], v[74:77]
	v_lshl_add_u64 v[244:245], v[202:203], 0, s[2:3]
	v_mfma_f32_16x16x32_bf16 v[78:81], v[158:161], v[146:149], v[78:81]
	v_lshl_add_u64 v[244:245], v[244:245], 0, s[12:13]
	v_mfma_f32_16x16x32_bf16 v[70:73], v[158:161], v[150:153], v[70:73]
	s_add_i32 m0, s21, 0x2000
	s_waitcnt lgkmcnt(2)
	v_mfma_f32_16x16x32_bf16 v[10:13], v[154:157], v[138:141], v[10:13]
	global_load_lds_dwordx4 v[244:245], off
	v_mfma_f32_16x16x32_bf16 v[62:65], v[154:157], v[142:145], v[62:65]
	v_lshl_add_u64 v[244:245], v[204:205], 0, s[2:3]
	v_mfma_f32_16x16x32_bf16 v[66:69], v[154:157], v[146:149], v[66:69]
	v_lshl_add_u64 v[244:245], v[244:245], 0, s[12:13]
	v_mfma_f32_16x16x32_bf16 v[58:61], v[154:157], v[150:153], v[58:61]
	s_add_i32 m0, s21, 0x3000
	s_waitcnt lgkmcnt(1)
	v_mfma_f32_16x16x32_bf16 v[6:9], v[134:137], v[138:141], v[6:9]
	global_load_lds_dwordx4 v[244:245], off
	v_mfma_f32_16x16x32_bf16 v[50:53], v[134:137], v[142:145], v[50:53]
	v_lshl_add_u64 v[244:245], v[208:209], 0, s[4:5]
	v_mfma_f32_16x16x32_bf16 v[54:57], v[134:137], v[146:149], v[54:57]
	s_add_i32 m0, s21, 0x4000
	v_mfma_f32_16x16x32_bf16 v[46:49], v[134:137], v[150:153], v[46:49]
	global_load_lds_dwordx4 v[244:245], off
	s_waitcnt lgkmcnt(0)
	v_mfma_f32_16x16x32_bf16 v[2:5], v[130:133], v[138:141], v[2:5]
	v_lshl_add_u64 v[244:245], v[206:207], 0, s[4:5]
	v_mfma_f32_16x16x32_bf16 v[34:37], v[130:133], v[142:145], v[34:37]
	s_add_i32 m0, s21, 0x5000
	v_mfma_f32_16x16x32_bf16 v[42:45], v[130:133], v[146:149], v[42:45]
	global_load_lds_dwordx4 v[244:245], off
	v_mfma_f32_16x16x32_bf16 v[30:33], v[130:133], v[150:153], v[30:33]
	s_setprio 0
	s_branch .Lgt_tail_12

;     ...
;   for (int kt = 0; kt < nk; ++kt) {
;     if (NST == 4 && kt + 2 < nk) asm volatile("s_waitcnt vmcnt(%0)" ::"n"(2 * NLD) : "memory");
;     else if (kt + 1 < nk) asm volatile("s_waitcnt vmcnt(%0)" ::"n"(NLD) : "memory");
;     else asm volatile("s_waitcnt vmcnt(0)" ::: "memory");
;     __builtin_amdgcn_s_barrier();
;     const char* st = smem + (kt % NST) * STAGE;
;     bf16x8 af[MS], bfr[4];
; #pragma unroll
;     for (int ms = 0; ms < MS; ++ms) af[ms] = *(const bf16x8*)(st + aoff_r + ms * 1024);
; #pragma unroll
;     for (int ns = 0; ns < 4; ++ns) bfr[ns] = *(const bf16x8*)(st + boff_r + ns * 1024);
;     asm volatile("" ::: "memory");
;     if (kt + NST - 1 < nk) ISSUE(kt + NST - 1)
;     __builtin_amdgcn_s_setprio(1);
; #pragma unroll
;     for (int ms = 0; ms < MS; ++ms)
; #pragma unroll
;       for (int ns = 0; ns < 4; ++ns) acc[ms][ns] = __builtin_amdgcn_mfma_f32_16x16x32_bf16(af[ms], bfr[ns], acc[ms][ns], 0, 0, 0);
;     __builtin_amdgcn_s_setprio(0);
.LBB0_2248:
	s_mul_hi_u32 s12, s22, 0xaaaaaaab
	s_lshr_b32 s12, s12, 1
	s_mul_i32 s12, s12, 0x12000
	v_subrev_u32_e32 v130, s12, v240
	v_add_u32_e32 v139, s21, v241
	v_add_u32_e32 v130, v139, v130
	v_subrev_u32_e32 v138, s12, v242
	v_add_u32_e32 v150, v139, v138
	s_barrier
	ds_read_b128 v[138:141], v150 offset:16384
	ds_read_b128 v[142:145], v150 offset:17408
	ds_read_b128 v[146:149], v150 offset:18432
	ds_read_b128 v[150:153], v150 offset:19456
	ds_read_b128 v[174:177], v130
	ds_read_b128 v[170:173], v130 offset:1024
	ds_read_b128 v[166:169], v130 offset:2048
	ds_read_b128 v[162:165], v130 offset:3072
	ds_read_b128 v[158:161], v130 offset:4096
	ds_read_b128 v[154:157], v130 offset:5120
	ds_read_b128 v[134:137], v130 offset:6144
	ds_read_b128 v[130:133], v130 offset:7168
	s_cmpk_gt_u32 s2, 0x55
	s_cbranch_scc1 .LBB0_2243
	s_mul_i32 s13, s20, 0xab
	s_bfe_u32 s13, s13, 0x70009
	s_mul_i32 s13, s13, 3
	s_add_i32 s2, s4, 0x4000
	s_sub_i32 s13, s20, s13
	s_and_b32 s2, s2, 0x1fc000
	s_and_b32 s13, s13, 0xff
	s_and_b32 s12, s4, 0x2000
	s_mulk_i32 s13, 0x6000
	s_lshl_b32 s2, s2, 1
	s_add_i32 s23, s19, s13
	s_setprio 1
	s_waitcnt lgkmcnt(7)
	v_mfma_f32_16x16x32_bf16 v[126:129], v[174:177], v[138:141], v[126:129]
	v_mfma_f32_16x16x32_bf16 v[122:125], v[174:177], v[142:145], v[122:125]
	v_mfma_f32_16x16x32_bf16 v[118:121], v[174:177], v[146:149], v[118:121]
	v_mfma_f32_16x16x32_bf16 v[114:117], v[174:177], v[150:153], v[114:117]
	s_waitcnt lgkmcnt(6)
	v_mfma_f32_16x16x32_bf16 v[110:113], v[170:173], v[138:141], v[110:113]
	v_mfma_f32_16x16x32_bf16 v[106:109], v[170:173], v[142:145], v[106:109]
	v_mfma_f32_16x16x32_bf16 v[102:105], v[170:173], v[146:149], v[102:105]
	v_mfma_f32_16x16x32_bf16 v[98:101], v[170:173], v[150:153], v[98:101]
	v_lshl_add_u64 v[244:245], v[194:195], 0, s[2:3]
	s_waitcnt lgkmcnt(5)
	v_mfma_f32_16x16x32_bf16 v[94:97], v[166:169], v[138:141], v[94:97]
	s_lshl_b32 s12, s12, 1
	v_mfma_f32_16x16x32_bf16 v[90:93], v[166:169], v[142:145], v[90:93]
	s_mov_b32 s13, s3
	v_mfma_f32_16x16x32_bf16 v[86:89], v[166:169], v[146:149], v[86:89]
	v_lshl_add_u64 v[244:245], v[244:245], 0, s[12:13]
	v_mfma_f32_16x16x32_bf16 v[82:85], v[166:169], v[150:153], v[82:85]
	s_mov_b32 m0, s23
	s_waitcnt lgkmcnt(4)
	v_mfma_f32_16x16x32_bf16 v[78:81], v[162:165], v[138:141], v[78:81]
	global_load_lds_dwordx4 v[244:245], off
	v_mfma_f32_16x16x32_bf16 v[74:77], v[162:165], v[142:145], v[74:77]
	v_lshl_add_u64 v[244:245], v[196:197], 0, s[2:3]
	v_mfma_f32_16x16x32_bf16 v[70:73], v[162:165], v[146:149], v[70:73]
	v_lshl_add_u64 v[244:245], v[244:245], 0, s[12:13]
	v_mfma_f32_16x16x32_bf16 v[66:69], v[162:165], v[150:153], v[66:69]
	s_add_i32 m0, s23, 0x1000
	s_waitcnt lgkmcnt(3)
	v_mfma_f32_16x16x32_bf16 v[62:65], v[158:161], v[138:141], v[62:65]
	global_load_lds_dwordx4 v[244:245], off
	v_mfma_f32_16x16x32_bf16 v[58:61], v[158:161], v[142:145], v[58:61]
	v_lshl_add_u64 v[244:245], v[198:199], 0, s[2:3]
	v_mfma_f32_16x16x32_bf16 v[54:57], v[158:161], v[146:149], v[54:57]
	v_lshl_add_u64 v[244:245], v[244:245], 0, s[12:13]
	v_mfma_f32_16x16x32_bf16 v[50:53], v[158:161], v[150:153], v[50:53]
	s_add_i32 m0, s23, 0x2000
	s_waitcnt lgkmcnt(2)
	v_mfma_f32_16x16x32_bf16 v[46:49], v[154:157], v[138:141], v[46:49]
	global_load_lds_dwordx4 v[244:245], off
	v_mfma_f32_16x16x32_bf16 v[42:45], v[154:157], v[142:145], v[42:45]
	v_lshl_add_u64 v[244:245], v[200:201], 0, s[2:3]
	v_mfma_f32_16x16x32_bf16 v[38:41], v[154:157], v[146:149], v[38:41]
	v_lshl_add_u64 v[244:245], v[244:245], 0, s[12:13]
	v_mfma_f32_16x16x32_bf16 v[34:37], v[154:157], v[150:153], v[34:37]
	s_add_i32 m0, s23, 0x3000
	s_waitcnt lgkmcnt(1)
	v_mfma_f32_16x16x32_bf16 v[30:33], v[134:137], v[138:141], v[30:33]
	global_load_lds_dwordx4 v[244:245], off
	v_mfma_f32_16x16x32_bf16 v[26:29], v[134:137], v[142:145], v[26:29]
	v_lshl_add_u64 v[244:245], v[202:203], 0, s[4:5]
	v_mfma_f32_16x16x32_bf16 v[22:25], v[134:137], v[146:149], v[22:25]
	s_add_i32 m0, s23, 0x4000
	v_mfma_f32_16x16x32_bf16 v[18:21], v[134:137], v[150:153], v[18:21]
	global_load_lds_dwordx4 v[244:245], off
	s_waitcnt lgkmcnt(0)
	v_mfma_f32_16x16x32_bf16 v[14:17], v[130:133], v[138:141], v[14:17]
	v_lshl_add_u64 v[244:245], v[204:205], 0, s[4:5]
	v_mfma_f32_16x16x32_bf16 v[10:13], v[130:133], v[142:145], v[10:13]
	s_add_i32 m0, s23, 0x5000
	v_mfma_f32_16x16x32_bf16 v[6:9], v[130:133], v[146:149], v[6:9]
	global_load_lds_dwordx4 v[244:245], off
	v_mfma_f32_16x16x32_bf16 v[2:5], v[130:133], v[150:153], v[2:5]
	s_setprio 0
	s_branch .Lgt_tail_13

;     ...
;   for (int kt = 0; kt < nk; ++kt) {
;     if (NST == 4 && kt + 2 < nk) asm volatile("s_waitcnt vmcnt(%0)" ::"n"(2 * NLD) : "memory");
;     else if (kt + 1 < nk) asm volatile("s_waitcnt vmcnt(%0)" ::"n"(NLD) : "memory");
;     else asm volatile("s_waitcnt vmcnt(0)" ::: "memory");
;     __builtin_amdgcn_s_barrier();
;     const char* st = smem + (kt % NST) * STAGE;
;     bf16x8 af[MS], bfr[4];
; #pragma unroll
;     for (int ms = 0; ms < MS; ++ms) af[ms] = *(const bf16x8*)(st + aoff_r + ms * 1024);
; #pragma unroll
;     for (int ns = 0; ns < 4; ++ns) bfr[ns] = *(const bf16x8*)(st + boff_r + ns * 1024);
;     asm volatile("" ::: "memory");
;     if (kt + NST - 1 < nk) ISSUE(kt + NST - 1)
;     __builtin_amdgcn_s_setprio(1);
; #pragma unroll
;     for (int ms = 0; ms < MS; ++ms)
; #pragma unroll
;       for (int ns = 0; ns < 4; ++ns) acc[ms][ns] = __builtin_amdgcn_mfma_f32_16x16x32_bf16(af[ms], bfr[ns], acc[ms][ns], 0, 0, 0);
;     __builtin_amdgcn_s_setprio(0);
.LBB0_2277:
	s_mul_hi_u32 s12, s22, 0xaaaaaaab
	s_lshr_b32 s12, s12, 1
	s_mul_i32 s12, s12, 0x12000
	v_subrev_u32_e32 v130, s12, v236
	v_add_u32_e32 v139, s21, v237
	v_add_u32_e32 v130, v139, v130
	v_subrev_u32_e32 v138, s12, v238
	v_add_u32_e32 v150, v139, v138
	s_barrier
	ds_read_b128 v[138:141], v150 offset:16384
	ds_read_b128 v[142:145], v150 offset:17408
	ds_read_b128 v[146:149], v150 offset:18432
	ds_read_b128 v[150:153], v150 offset:19456
	ds_read_b128 v[174:177], v130
	ds_read_b128 v[170:173], v130 offset:1024
	ds_read_b128 v[166:169], v130 offset:2048
	ds_read_b128 v[162:165], v130 offset:3072
	ds_read_b128 v[158:161], v130 offset:4096
	ds_read_b128 v[154:157], v130 offset:5120
	ds_read_b128 v[134:137], v130 offset:6144
	ds_read_b128 v[130:133], v130 offset:7168
	s_cmpk_gt_u32 s2, 0x55
	s_cbranch_scc1 .LBB0_2272
	s_mul_i32 s13, s20, 0xab
	s_bfe_u32 s13, s13, 0x70009
	s_mul_i32 s13, s13, 3
	s_add_i32 s2, s4, 0x4000
	s_sub_i32 s13, s20, s13
	s_and_b32 s2, s2, 0x1fc000
	s_and_b32 s13, s13, 0xff
	s_and_b32 s12, s4, 0x2000
	s_mulk_i32 s13, 0x6000
	s_lshl_b32 s2, s2, 1
	s_add_i32 s23, s19, s13
	s_setprio 1
	s_waitcnt lgkmcnt(7)
	v_mfma_f32_16x16x32_bf16 v[126:129], v[174:177], v[138:141], v[126:129]
	v_mfma_f32_16x16x32_bf16 v[122:125], v[174:177], v[142:145], v[122:125]
	v_mfma_f32_16x16x32_bf16 v[118:121], v[174:177], v[146:149], v[118:121]
	v_mfma_f32_16x16x32_bf16 v[114:117], v[174:177], v[150:153], v[114:117]
	s_waitcnt lgkmcnt(6)
	v_mfma_f32_16x16x32_bf16 v[110:113], v[170:173], v[138:141], v[110:113]
	v_mfma_f32_16x16x32_bf16 v[106:109], v[170:173], v[142:145], v[106:109]
	v_mfma_f32_16x16x32_bf16 v[102:105], v[170:173], v[146:149], v[102:105]
	v_mfma_f32_16x16x32_bf16 v[98:101], v[170:173], v[150:153], v[98:101]
	v_lshl_add_u64 v[240:241], v[194:195], 0, s[2:3]
	s_waitcnt lgkmcnt(5)
	v_mfma_f32_16x16x32_bf16 v[94:97], v[166:169], v[138:141], v[94:97]
	s_lshl_b32 s12, s12, 1
	v_mfma_f32_16x16x32_bf16 v[90:93], v[166:169], v[142:145], v[90:93]
	s_mov_b32 s13, s3
	v_mfma_f32_16x16x32_bf16 v[86:89], v[166:169], v[146:149], v[86:89]
	v_lshl_add_u64 v[240:241], v[240:241], 0, s[12:13]
	v_mfma_f32_16x16x32_bf16 v[82:85], v[166:169], v[150:153], v[82:85]
	s_mov_b32 m0, s23
	s_waitcnt lgkmcnt(4)
	v_mfma_f32_16x16x32_bf16 v[78:81], v[162:165], v[138:141], v[78:81]
	global_load_lds_dwordx4 v[240:241], off
	v_mfma_f32_16x16x32_bf16 v[74:77], v[162:165], v[142:145], v[74:77]
	v_lshl_add_u64 v[240:241], v[196:197], 0, s[2:3]
	v_mfma_f32_16x16x32_bf16 v[70:73], v[162:165], v[146:149], v[70:73]
	v_lshl_add_u64 v[240:241], v[240:241], 0, s[12:13]
	v_mfma_f32_16x16x32_bf16 v[66:69], v[162:165], v[150:153], v[66:69]
	s_add_i32 m0, s23, 0x1000
	s_waitcnt lgkmcnt(3)
	v_mfma_f32_16x16x32_bf16 v[62:65], v[158:161], v[138:141], v[62:65]
	global_load_lds_dwordx4 v[240:241], off
	v_mfma_f32_16x16x32_bf16 v[58:61], v[158:161], v[142:145], v[58:61]
	v_lshl_add_u64 v[240:241], v[198:199], 0, s[2:3]
	v_mfma_f32_16x16x32_bf16 v[54:57], v[158:161], v[146:149], v[54:57]
	v_lshl_add_u64 v[240:241], v[240:241], 0, s[12:13]
	v_mfma_f32_16x16x32_bf16 v[50:53], v[158:161], v[150:153], v[50:53]
	s_add_i32 m0, s23, 0x2000
	s_waitcnt lgkmcnt(2)
	v_mfma_f32_16x16x32_bf16 v[46:49], v[154:157], v[138:141], v[46:49]
	global_load_lds_dwordx4 v[240:241], off
	v_mfma_f32_16x16x32_bf16 v[42:45], v[154:157], v[142:145], v[42:45]
	v_lshl_add_u64 v[240:241], v[200:201], 0, s[2:3]
	v_mfma_f32_16x16x32_bf16 v[38:41], v[154:157], v[146:149], v[38:41]
	v_lshl_add_u64 v[240:241], v[240:241], 0, s[12:13]
	v_mfma_f32_16x16x32_bf16 v[34:37], v[154:157], v[150:153], v[34:37]
	s_add_i32 m0, s23, 0x3000
	s_waitcnt lgkmcnt(1)
	v_mfma_f32_16x16x32_bf16 v[30:33], v[134:137], v[138:141], v[30:33]
	global_load_lds_dwordx4 v[240:241], off
	v_mfma_f32_16x16x32_bf16 v[26:29], v[134:137], v[142:145], v[26:29]
	v_lshl_add_u64 v[240:241], v[202:203], 0, s[4:5]
	v_mfma_f32_16x16x32_bf16 v[22:25], v[134:137], v[146:149], v[22:25]
	s_add_i32 m0, s23, 0x4000
	v_mfma_f32_16x16x32_bf16 v[18:21], v[134:137], v[150:153], v[18:21]
	global_load_lds_dwordx4 v[240:241], off
	s_waitcnt lgkmcnt(0)
	v_mfma_f32_16x16x32_bf16 v[14:17], v[130:133], v[138:141], v[14:17]
	v_lshl_add_u64 v[240:241], v[204:205], 0, s[4:5]
	v_mfma_f32_16x16x32_bf16 v[10:13], v[130:133], v[142:145], v[10:13]
	s_add_i32 m0, s23, 0x5000
	v_mfma_f32_16x16x32_bf16 v[6:9], v[130:133], v[146:149], v[6:9]
	global_load_lds_dwordx4 v[240:241], off
	v_mfma_f32_16x16x32_bf16 v[2:5], v[130:133], v[150:153], v[2:5]
	s_setprio 0
	s_branch .Lgt_tail_14

;     ...
;   for (int kt = 0; kt < nk; ++kt) {
;     if (NST == 4 && kt + 2 < nk) asm volatile("s_waitcnt vmcnt(%0)" ::"n"(2 * NLD) : "memory");
;     else if (kt + 1 < nk) asm volatile("s_waitcnt vmcnt(%0)" ::"n"(NLD) : "memory");
;     else asm volatile("s_waitcnt vmcnt(0)" ::: "memory");
;     __builtin_amdgcn_s_barrier();
;     const char* st = smem + (kt % NST) * STAGE;
;     bf16x8 af[MS], bfr[4];
; #pragma unroll
;     for (int ms = 0; ms < MS; ++ms) af[ms] = *(const bf16x8*)(st + aoff_r + ms * 1024);
; #pragma unroll
;     for (int ns = 0; ns < 4; ++ns) bfr[ns] = *(const bf16x8*)(st + boff_r + ns * 1024);
;     asm volatile("" ::: "memory");
;     if (kt + NST - 1 < nk) ISSUE(kt + NST - 1)
;     __builtin_amdgcn_s_setprio(1);
; #pragma unroll
;     for (int ms = 0; ms < MS; ++ms)
; #pragma unroll
;       for (int ns = 0; ns < 4; ++ns) acc[ms][ns] = __builtin_amdgcn_mfma_f32_16x16x32_bf16(af[ms], bfr[ns], acc[ms][ns], 0, 0, 0);
;     __builtin_amdgcn_s_setprio(0);
.LBB0_2312:
	s_mul_hi_u32 s8, s16, 0xaaaaaaab
	s_lshr_b32 s8, s8, 1
	s_mul_i32 s8, s8, 0x12000
	v_subrev_u32_e32 v130, s8, v187
	v_add_u32_e32 v139, s15, v189
	v_add_u32_e32 v130, v139, v130
	v_subrev_u32_e32 v138, s8, v238
	v_add_u32_e32 v150, v139, v138
	s_barrier
	ds_read_b128 v[138:141], v150 offset:16384
	ds_read_b128 v[142:145], v150 offset:17408
	ds_read_b128 v[146:149], v150 offset:18432
	ds_read_b128 v[150:153], v150 offset:19456
	ds_read_b128 v[174:177], v130
	ds_read_b128 v[170:173], v130 offset:1024
	ds_read_b128 v[166:169], v130 offset:2048
	ds_read_b128 v[162:165], v130 offset:3072
	ds_read_b128 v[158:161], v130 offset:4096
	ds_read_b128 v[154:157], v130 offset:5120
	ds_read_b128 v[134:137], v130 offset:6144
	ds_read_b128 v[130:133], v130 offset:7168
	s_cmp_gt_u32 s2, 29
	s_cbranch_scc1 .LBB0_2307
	s_mul_i32 s9, s13, 0xab
	s_bfe_u32 s9, s9, 0x70009
	s_mul_i32 s9, s9, 3
	s_add_i32 s2, s4, 0x4000
	s_sub_i32 s9, s13, s9
	s_and_b32 s2, s2, 0x7c000
	s_and_b32 s9, s9, 0xff
	s_and_b32 s8, s4, 0x2000
	s_mulk_i32 s9, 0x6000
	s_lshl_b32 s2, s2, 1
	s_add_i32 s17, s11, s9
	s_setprio 1
	s_waitcnt lgkmcnt(7)
	v_mfma_f32_16x16x32_bf16 v[126:129], v[174:177], v[138:141], v[126:129]
	v_mfma_f32_16x16x32_bf16 v[122:125], v[174:177], v[142:145], v[122:125]
	v_mfma_f32_16x16x32_bf16 v[118:121], v[174:177], v[146:149], v[118:121]
	v_mfma_f32_16x16x32_bf16 v[114:117], v[174:177], v[150:153], v[114:117]
	s_waitcnt lgkmcnt(6)
	v_mfma_f32_16x16x32_bf16 v[110:113], v[170:173], v[138:141], v[110:113]
	v_mfma_f32_16x16x32_bf16 v[106:109], v[170:173], v[142:145], v[106:109]
	v_mfma_f32_16x16x32_bf16 v[102:105], v[170:173], v[146:149], v[102:105]
	v_mfma_f32_16x16x32_bf16 v[98:101], v[170:173], v[150:153], v[98:101]
	v_lshl_add_u64 v[240:241], v[198:199], 0, s[2:3]
	s_waitcnt lgkmcnt(5)
	v_mfma_f32_16x16x32_bf16 v[94:97], v[166:169], v[138:141], v[94:97]
	s_lshl_b32 s8, s8, 1
	v_mfma_f32_16x16x32_bf16 v[90:93], v[166:169], v[142:145], v[90:93]
	s_mov_b32 s9, s3
	v_mfma_f32_16x16x32_bf16 v[86:89], v[166:169], v[146:149], v[86:89]
	v_lshl_add_u64 v[240:241], v[240:241], 0, s[8:9]
	v_mfma_f32_16x16x32_bf16 v[82:85], v[166:169], v[150:153], v[82:85]
	s_mov_b32 m0, s17
	s_waitcnt lgkmcnt(4)
	v_mfma_f32_16x16x32_bf16 v[78:81], v[162:165], v[138:141], v[78:81]
	global_load_lds_dwordx4 v[240:241], off
	v_mfma_f32_16x16x32_bf16 v[74:77], v[162:165], v[142:145], v[74:77]
	v_lshl_add_u64 v[240:241], v[200:201], 0, s[2:3]
	v_mfma_f32_16x16x32_bf16 v[70:73], v[162:165], v[146:149], v[70:73]
	v_lshl_add_u64 v[240:241], v[240:241], 0, s[8:9]
	v_mfma_f32_16x16x32_bf16 v[66:69], v[162:165], v[150:153], v[66:69]
	s_add_i32 m0, s17, 0x1000
	s_waitcnt lgkmcnt(3)
	v_mfma_f32_16x16x32_bf16 v[62:65], v[158:161], v[138:141], v[62:65]
	global_load_lds_dwordx4 v[240:241], off
	v_mfma_f32_16x16x32_bf16 v[58:61], v[158:161], v[142:145], v[58:61]
	v_lshl_add_u64 v[240:241], v[202:203], 0, s[2:3]
	v_mfma_f32_16x16x32_bf16 v[54:57], v[158:161], v[146:149], v[54:57]
	v_lshl_add_u64 v[240:241], v[240:241], 0, s[8:9]
	v_mfma_f32_16x16x32_bf16 v[50:53], v[158:161], v[150:153], v[50:53]
	s_add_i32 m0, s17, 0x2000
	s_waitcnt lgkmcnt(2)
	v_mfma_f32_16x16x32_bf16 v[46:49], v[154:157], v[138:141], v[46:49]
	global_load_lds_dwordx4 v[240:241], off
	v_mfma_f32_16x16x32_bf16 v[42:45], v[154:157], v[142:145], v[42:45]
	v_lshl_add_u64 v[240:241], v[204:205], 0, s[2:3]
	v_mfma_f32_16x16x32_bf16 v[38:41], v[154:157], v[146:149], v[38:41]
	v_lshl_add_u64 v[240:241], v[240:241], 0, s[8:9]
	v_mfma_f32_16x16x32_bf16 v[34:37], v[154:157], v[150:153], v[34:37]
	s_add_i32 m0, s17, 0x3000
	s_waitcnt lgkmcnt(1)
	v_mfma_f32_16x16x32_bf16 v[30:33], v[134:137], v[138:141], v[30:33]
	global_load_lds_dwordx4 v[240:241], off
	v_mfma_f32_16x16x32_bf16 v[26:29], v[134:137], v[142:145], v[26:29]
	v_lshl_add_u64 v[240:241], v[208:209], 0, s[4:5]
	v_mfma_f32_16x16x32_bf16 v[22:25], v[134:137], v[146:149], v[22:25]
	s_add_i32 m0, s17, 0x4000
	v_mfma_f32_16x16x32_bf16 v[18:21], v[134:137], v[150:153], v[18:21]
	global_load_lds_dwordx4 v[240:241], off
	s_waitcnt lgkmcnt(0)
	v_mfma_f32_16x16x32_bf16 v[14:17], v[130:133], v[138:141], v[14:17]
	v_lshl_add_u64 v[240:241], v[206:207], 0, s[4:5]
	v_mfma_f32_16x16x32_bf16 v[10:13], v[130:133], v[142:145], v[10:13]
	s_add_i32 m0, s17, 0x5000
	v_mfma_f32_16x16x32_bf16 v[6:9], v[130:133], v[146:149], v[6:9]
	global_load_lds_dwordx4 v[240:241], off
	v_mfma_f32_16x16x32_bf16 v[2:5], v[130:133], v[150:153], v[2:5]
	s_setprio 0
	s_branch .Lgt_tail_15

;     ...
;   for (int kt = 0; kt < nk; ++kt) {
;     if (NST == 4 && kt + 2 < nk) asm volatile("s_waitcnt vmcnt(%0)" ::"n"(2 * NLD) : "memory");
;     else if (kt + 1 < nk) asm volatile("s_waitcnt vmcnt(%0)" ::"n"(NLD) : "memory");
;     else asm volatile("s_waitcnt vmcnt(0)" ::: "memory");
;     __builtin_amdgcn_s_barrier();
;     const char* st = smem + (kt % NST) * STAGE;
;     bf16x8 af[MS], bfr[4];
; #pragma unroll
;     for (int ms = 0; ms < MS; ++ms) af[ms] = *(const bf16x8*)(st + aoff_r + ms * 1024);
; #pragma unroll
;     for (int ns = 0; ns < 4; ++ns) bfr[ns] = *(const bf16x8*)(st + boff_r + ns * 1024);
;     asm volatile("" ::: "memory");
;     if (kt + NST - 1 < nk) ISSUE(kt + NST - 1)
;     __builtin_amdgcn_s_setprio(1);
; #pragma unroll
;     for (int ms = 0; ms < MS; ++ms)
; #pragma unroll
;       for (int ns = 0; ns < 4; ++ns) acc[ms][ns] = __builtin_amdgcn_mfma_f32_16x16x32_bf16(af[ms], bfr[ns], acc[ms][ns], 0, 0, 0);
;     __builtin_amdgcn_s_setprio(0);
.LBB0_2341:
	s_mul_hi_u32 s8, s16, 0xaaaaaaab
	s_lshr_b32 s8, s8, 1
	s_mul_i32 s8, s8, 0x12000
	v_subrev_u32_e32 v130, s8, v178
	v_add_u32_e32 v139, s15, v187
	v_add_u32_e32 v130, v139, v130
	v_subrev_u32_e32 v138, s8, v189
	v_add_u32_e32 v150, v139, v138
	s_barrier
	ds_read_b128 v[138:141], v150 offset:16384
	ds_read_b128 v[142:145], v150 offset:17408
	ds_read_b128 v[146:149], v150 offset:18432
	ds_read_b128 v[150:153], v150 offset:19456
	ds_read_b128 v[174:177], v130
	ds_read_b128 v[170:173], v130 offset:1024
	ds_read_b128 v[166:169], v130 offset:2048
	ds_read_b128 v[162:165], v130 offset:3072
	ds_read_b128 v[158:161], v130 offset:4096
	ds_read_b128 v[154:157], v130 offset:5120
	ds_read_b128 v[134:137], v130 offset:6144
	ds_read_b128 v[130:133], v130 offset:7168
	s_cmp_gt_u32 s2, 29
	s_cbranch_scc1 .LBB0_2336
	s_mul_i32 s9, s13, 0xab
	s_bfe_u32 s9, s9, 0x70009
	s_mul_i32 s9, s9, 3
	s_add_i32 s2, s4, 0x4000
	s_sub_i32 s9, s13, s9
	s_and_b32 s2, s2, 0x7c000
	s_and_b32 s9, s9, 0xff
	s_and_b32 s8, s4, 0x2000
	s_mulk_i32 s9, 0x6000
	s_lshl_b32 s2, s2, 1
	s_add_i32 s17, s11, s9
	s_setprio 1
	s_waitcnt lgkmcnt(7)
	v_mfma_f32_16x16x32_bf16 v[126:129], v[174:177], v[138:141], v[126:129]
	v_mfma_f32_16x16x32_bf16 v[122:125], v[174:177], v[142:145], v[122:125]
	v_mfma_f32_16x16x32_bf16 v[118:121], v[174:177], v[146:149], v[118:121]
	v_mfma_f32_16x16x32_bf16 v[114:117], v[174:177], v[150:153], v[114:117]
	s_waitcnt lgkmcnt(6)
	v_mfma_f32_16x16x32_bf16 v[110:113], v[170:173], v[138:141], v[110:113]
	v_mfma_f32_16x16x32_bf16 v[106:109], v[170:173], v[142:145], v[106:109]
	v_mfma_f32_16x16x32_bf16 v[102:105], v[170:173], v[146:149], v[102:105]
	v_mfma_f32_16x16x32_bf16 v[98:101], v[170:173], v[150:153], v[98:101]
	v_lshl_add_u64 v[236:237], v[198:199], 0, s[2:3]
	s_waitcnt lgkmcnt(5)
	v_mfma_f32_16x16x32_bf16 v[94:97], v[166:169], v[138:141], v[94:97]
	s_lshl_b32 s8, s8, 1
	v_mfma_f32_16x16x32_bf16 v[90:93], v[166:169], v[142:145], v[90:93]
	s_mov_b32 s9, s3
	v_mfma_f32_16x16x32_bf16 v[86:89], v[166:169], v[146:149], v[86:89]
	v_lshl_add_u64 v[236:237], v[236:237], 0, s[8:9]
	v_mfma_f32_16x16x32_bf16 v[82:85], v[166:169], v[150:153], v[82:85]
	s_mov_b32 m0, s17
	s_waitcnt lgkmcnt(4)
	v_mfma_f32_16x16x32_bf16 v[78:81], v[162:165], v[138:141], v[78:81]
	global_load_lds_dwordx4 v[236:237], off
	v_mfma_f32_16x16x32_bf16 v[74:77], v[162:165], v[142:145], v[74:77]
	v_lshl_add_u64 v[236:237], v[200:201], 0, s[2:3]
	v_mfma_f32_16x16x32_bf16 v[70:73], v[162:165], v[146:149], v[70:73]
	v_lshl_add_u64 v[236:237], v[236:237], 0, s[8:9]
	v_mfma_f32_16x16x32_bf16 v[66:69], v[162:165], v[150:153], v[66:69]
	s_add_i32 m0, s17, 0x1000
	s_waitcnt lgkmcnt(3)
	v_mfma_f32_16x16x32_bf16 v[62:65], v[158:161], v[138:141], v[62:65]
	global_load_lds_dwordx4 v[236:237], off
	v_mfma_f32_16x16x32_bf16 v[58:61], v[158:161], v[142:145], v[58:61]
	v_lshl_add_u64 v[236:237], v[202:203], 0, s[2:3]
	v_mfma_f32_16x16x32_bf16 v[54:57], v[158:161], v[146:149], v[54:57]
	v_lshl_add_u64 v[236:237], v[236:237], 0, s[8:9]
	v_mfma_f32_16x16x32_bf16 v[50:53], v[158:161], v[150:153], v[50:53]
	s_add_i32 m0, s17, 0x2000
	s_waitcnt lgkmcnt(2)
	v_mfma_f32_16x16x32_bf16 v[46:49], v[154:157], v[138:141], v[46:49]
	global_load_lds_dwordx4 v[236:237], off
	v_mfma_f32_16x16x32_bf16 v[42:45], v[154:157], v[142:145], v[42:45]
	v_lshl_add_u64 v[236:237], v[204:205], 0, s[2:3]
	v_mfma_f32_16x16x32_bf16 v[38:41], v[154:157], v[146:149], v[38:41]
	v_lshl_add_u64 v[236:237], v[236:237], 0, s[8:9]
	v_mfma_f32_16x16x32_bf16 v[34:37], v[154:157], v[150:153], v[34:37]
	s_add_i32 m0, s17, 0x3000
	s_waitcnt lgkmcnt(1)
	v_mfma_f32_16x16x32_bf16 v[30:33], v[134:137], v[138:141], v[30:33]
	global_load_lds_dwordx4 v[236:237], off
	v_mfma_f32_16x16x32_bf16 v[26:29], v[134:137], v[142:145], v[26:29]
	v_lshl_add_u64 v[236:237], v[208:209], 0, s[4:5]
	v_mfma_f32_16x16x32_bf16 v[22:25], v[134:137], v[146:149], v[22:25]
	s_add_i32 m0, s17, 0x4000
	v_mfma_f32_16x16x32_bf16 v[18:21], v[134:137], v[150:153], v[18:21]
	global_load_lds_dwordx4 v[236:237], off
	s_waitcnt lgkmcnt(0)
	v_mfma_f32_16x16x32_bf16 v[14:17], v[130:133], v[138:141], v[14:17]
	v_lshl_add_u64 v[236:237], v[206:207], 0, s[4:5]
	v_mfma_f32_16x16x32_bf16 v[10:13], v[130:133], v[142:145], v[10:13]
	s_add_i32 m0, s17, 0x5000
	v_mfma_f32_16x16x32_bf16 v[6:9], v[130:133], v[146:149], v[6:9]
	global_load_lds_dwordx4 v[236:237], off
	v_mfma_f32_16x16x32_bf16 v[2:5], v[130:133], v[150:153], v[2:5]
	s_setprio 0
	s_branch .Lgt_tail_16
